# adds peeled first K-iteration with C=0 per GEMM unit (removes 128 accumulator-zeroing v_mov per unit) on top of saddr-form loads
# speedup vs baseline: 1.0110x; 1.0062x over previous
.LBB0_200:
	s_ashr_i32 s23, s22, 31
	s_lshl_b64 s[6:7], s[22:23], 20
	s_add_u32 s6, s29, s6
	s_addc_u32 s7, s34, s7
	s_ashr_i32 s25, s24, 31
	s_lshl_b64 s[36:37], s[24:25], 1
	s_add_u32 s6, s6, s36
	s_addc_u32 s7, s7, s37
	s_and_b64 s[44:45], s[52:53], exec
	s_cselect_b32 s23, s7, s43
	s_cselect_b32 s25, s6, s42
	s_ashr_i32 s27, s26, 31
	s_lshl_b64 s[44:45], s[26:27], 20
	s_add_u32 s27, s35, s44
	s_addc_u32 s41, s54, s45
	s_add_u32 s36, s27, s36
	s_addc_u32 s37, s41, s37
	s_and_b64 s[44:45], s[52:53], exec
	s_cselect_b32 s27, s37, s51
	s_cselect_b32 s41, s36, s50
	s_add_i32 s44, s33, -2
	s_add_u32 s42, s42, 0x80080
	s_addc_u32 s43, s43, 0
	s_add_u32 s45, s50, 0x100
	s_addc_u32 s58, s51, 0
	s_mov_b32 s50, 0
	v_add_u32_e32 v253, 0x10000, v147
	s_add_i32 s59, s50, 2
	s_add_u32 s51, s42, 0xfff80080
	s_addc_u32 s52, s43, -1
	s_add_i32 s70, 0, 0x10000
	s_cmp_eq_u32 s44, s50
	s_cselect_b32 s53, s23, s52
	s_cselect_b32 s52, s25, s51
	s_cselect_b32 s51, s27, s58
	s_cselect_b32 s50, s41, s45
	s_add_i32 s74, 0, 0x14000
	ds_read_b128 v[150:153], v253
	ds_read_b128 v[154:157], v253 offset:1024
	ds_read_b128 v[158:161], v253 offset:2048
	ds_read_b128 v[162:165], v253 offset:3072
	ds_read_b128 v[166:169], v253 offset:16384
	ds_read_b128 v[170:173], v253 offset:17408
	ds_read_b128 v[174:177], v253 offset:18432
	ds_read_b128 v[178:181], v253 offset:19456
	s_add_i32 m0, s31, 0xc000
	ds_read_b128 v[182:185], v149
	ds_read_b128 v[186:189], v149 offset:1024
	ds_read_b128 v[190:193], v149 offset:2048
	ds_read_b128 v[204:207], v149 offset:3072
	ds_read_b128 v[208:211], v149 offset:4096
	ds_read_b128 v[212:215], v149 offset:5120
	ds_read_b128 v[216:219], v149 offset:6144
	ds_read_b128 v[220:223], v149 offset:7168
	global_load_lds_dwordx4 v140, s[42:43]
	s_add_i32 m0, s31, 0xe000
	s_nop 0
	global_load_lds_dwordx4 v142, s[42:43]
	s_waitcnt vmcnt(8)
	s_waitcnt lgkmcnt(0)
	s_barrier
	s_setprio 1
	s_waitcnt lgkmcnt(0)
	v_mfma_f32_16x16x32_bf16 v[126:129], v[150:153], v[182:185], 0
	v_mfma_f32_16x16x32_bf16 v[122:125], v[158:161], v[182:185], 0
	v_mfma_f32_16x16x32_bf16 v[114:117], v[150:153], v[190:193], 0
	v_mfma_f32_16x16x32_bf16 v[106:109], v[158:161], v[190:193], 0
	v_mfma_f32_16x16x32_bf16 v[98:101], v[150:153], v[208:211], 0
	v_mfma_f32_16x16x32_bf16 v[90:93], v[158:161], v[208:211], 0
	v_mfma_f32_16x16x32_bf16 v[82:85], v[150:153], v[216:219], 0
	v_mfma_f32_16x16x32_bf16 v[74:77], v[158:161], v[216:219], 0
	v_mfma_f32_16x16x32_bf16 v[126:129], v[154:157], v[186:189], v[126:129]
	v_mfma_f32_16x16x32_bf16 v[122:125], v[162:165], v[186:189], v[122:125]
	v_mfma_f32_16x16x32_bf16 v[114:117], v[154:157], v[204:207], v[114:117]
	v_mfma_f32_16x16x32_bf16 v[106:109], v[162:165], v[204:207], v[106:109]
	v_mfma_f32_16x16x32_bf16 v[98:101], v[154:157], v[212:215], v[98:101]
	v_mfma_f32_16x16x32_bf16 v[90:93], v[162:165], v[212:215], v[90:93]
	v_mfma_f32_16x16x32_bf16 v[82:85], v[154:157], v[220:223], v[82:85]
	v_mfma_f32_16x16x32_bf16 v[74:77], v[162:165], v[220:223], v[74:77]
	s_setprio 0
	s_setprio 1
	v_mfma_f32_16x16x32_bf16 v[118:121], v[166:169], v[182:185], 0
	v_mfma_f32_16x16x32_bf16 v[110:113], v[174:177], v[182:185], 0
	v_mfma_f32_16x16x32_bf16 v[102:105], v[166:169], v[190:193], 0
	v_mfma_f32_16x16x32_bf16 v[94:97], v[174:177], v[190:193], 0
	v_mfma_f32_16x16x32_bf16 v[86:89], v[166:169], v[208:211], 0
	v_mfma_f32_16x16x32_bf16 v[78:81], v[174:177], v[208:211], 0
	v_mfma_f32_16x16x32_bf16 v[70:73], v[166:169], v[216:219], 0
	v_mfma_f32_16x16x32_bf16 v[66:69], v[174:177], v[216:219], 0
	v_mfma_f32_16x16x32_bf16 v[118:121], v[170:173], v[186:189], v[118:121]
	v_mfma_f32_16x16x32_bf16 v[110:113], v[178:181], v[186:189], v[110:113]
	v_mfma_f32_16x16x32_bf16 v[102:105], v[170:173], v[204:207], v[102:105]
	v_mfma_f32_16x16x32_bf16 v[94:97], v[178:181], v[204:207], v[94:97]
	v_mfma_f32_16x16x32_bf16 v[86:89], v[170:173], v[212:215], v[86:89]
	v_mfma_f32_16x16x32_bf16 v[78:81], v[178:181], v[212:215], v[78:81]
	v_mfma_f32_16x16x32_bf16 v[70:73], v[170:173], v[220:223], v[70:73]
	v_mfma_f32_16x16x32_bf16 v[66:69], v[178:181], v[220:223], v[66:69]
	s_setprio 0
	s_barrier
	s_add_i32 s70, s70, s55
	s_mov_b32 m0, s70
	ds_read_b128 v[182:185], v149 offset:16384
	ds_read_b128 v[186:189], v149 offset:17408
	ds_read_b128 v[190:193], v149 offset:18432
	ds_read_b128 v[204:207], v149 offset:19456
	ds_read_b128 v[208:211], v149 offset:20480
	ds_read_b128 v[212:215], v149 offset:21504
	ds_read_b128 v[216:219], v149 offset:22528
	ds_read_b128 v[220:223], v149 offset:23552
	global_load_lds_dwordx4 v0, s[50:51]
	s_add_i32 m0, s70, 0x2000
	s_add_u32 s70, s50, 0x80000
	s_addc_u32 s71, s51, 0
	s_add_i32 s74, s74, s55
	global_load_lds_dwordx4 v134, s[50:51]
	s_mov_b32 m0, s74
	s_nop 0
	global_load_lds_dwordx4 v0, s[70:71]
	s_add_i32 m0, s74, 0x2000
	s_nop 0
	global_load_lds_dwordx4 v134, s[70:71]
	s_mov_b32 m0, s31
	s_nop 0
	global_load_lds_dwordx4 v130, s[52:53]
	s_mov_b32 m0, s39
	s_nop 0
	global_load_lds_dwordx4 v132, s[52:53]
	s_waitcnt vmcnt(8)
	s_waitcnt lgkmcnt(0)
	s_barrier
	s_setprio 1
	s_waitcnt lgkmcnt(0)
	v_mfma_f32_16x16x32_bf16 v[62:65], v[150:153], v[182:185], 0
	v_mfma_f32_16x16x32_bf16 v[58:61], v[158:161], v[182:185], 0
	v_mfma_f32_16x16x32_bf16 v[50:53], v[150:153], v[190:193], 0
	v_mfma_f32_16x16x32_bf16 v[42:45], v[158:161], v[190:193], 0
	v_mfma_f32_16x16x32_bf16 v[34:37], v[150:153], v[208:211], 0
	v_mfma_f32_16x16x32_bf16 v[26:29], v[158:161], v[208:211], 0
	v_mfma_f32_16x16x32_bf16 v[18:21], v[150:153], v[216:219], 0
	v_mfma_f32_16x16x32_bf16 v[10:13], v[158:161], v[216:219], 0
	v_mfma_f32_16x16x32_bf16 v[62:65], v[154:157], v[186:189], v[62:65]
	v_mfma_f32_16x16x32_bf16 v[58:61], v[162:165], v[186:189], v[58:61]
	v_mfma_f32_16x16x32_bf16 v[50:53], v[154:157], v[204:207], v[50:53]
	v_mfma_f32_16x16x32_bf16 v[42:45], v[162:165], v[204:207], v[42:45]
	v_mfma_f32_16x16x32_bf16 v[34:37], v[154:157], v[212:215], v[34:37]
	v_mfma_f32_16x16x32_bf16 v[26:29], v[162:165], v[212:215], v[26:29]
	v_mfma_f32_16x16x32_bf16 v[18:21], v[154:157], v[220:223], v[18:21]
	v_mfma_f32_16x16x32_bf16 v[10:13], v[162:165], v[220:223], v[10:13]
	s_setprio 0
	s_setprio 1
	v_mfma_f32_16x16x32_bf16 v[54:57], v[166:169], v[182:185], 0
	v_mfma_f32_16x16x32_bf16 v[46:49], v[174:177], v[182:185], 0
	v_mfma_f32_16x16x32_bf16 v[38:41], v[166:169], v[190:193], 0
	v_mfma_f32_16x16x32_bf16 v[30:33], v[174:177], v[190:193], 0
	v_mfma_f32_16x16x32_bf16 v[22:25], v[166:169], v[208:211], 0
	v_mfma_f32_16x16x32_bf16 v[14:17], v[174:177], v[208:211], 0
	v_mfma_f32_16x16x32_bf16 v[6:9], v[166:169], v[216:219], 0
	v_mfma_f32_16x16x32_bf16 v[2:5], v[174:177], v[216:219], 0
	v_mfma_f32_16x16x32_bf16 v[54:57], v[170:173], v[186:189], v[54:57]
	v_mfma_f32_16x16x32_bf16 v[46:49], v[178:181], v[186:189], v[46:49]
	v_mfma_f32_16x16x32_bf16 v[38:41], v[170:173], v[204:207], v[38:41]
	v_mfma_f32_16x16x32_bf16 v[30:33], v[178:181], v[204:207], v[30:33]
	v_mfma_f32_16x16x32_bf16 v[22:25], v[170:173], v[212:215], v[22:25]
	v_mfma_f32_16x16x32_bf16 v[14:17], v[178:181], v[212:215], v[14:17]
	v_mfma_f32_16x16x32_bf16 v[6:9], v[170:173], v[220:223], v[6:9]
	v_mfma_f32_16x16x32_bf16 v[2:5], v[178:181], v[220:223], v[2:5]
	s_setprio 0
	s_barrier
	s_add_i32 s70, 0, 0x18000
	s_add_i32 s71, 0, 0x1c000
	ds_read_b128 v[150:153], v253 offset:32768
	ds_read_b128 v[154:157], v253 offset:33792
	ds_read_b128 v[158:161], v253 offset:34816
	ds_read_b128 v[162:165], v253 offset:35840
	ds_read_b128 v[166:169], v253 offset:49152
	ds_read_b128 v[170:173], v253 offset:50176
	ds_read_b128 v[174:177], v253 offset:51200
	ds_read_b128 v[178:181], v253 offset:52224
	s_add_u32 s52, s52, 0x80000
	s_addc_u32 s53, s53, 0
	s_mov_b32 m0, s56
	ds_read_b128 v[182:185], v149 offset:32768
	ds_read_b128 v[186:189], v149 offset:33792
	ds_read_b128 v[190:193], v149 offset:34816
	ds_read_b128 v[204:207], v149 offset:35840
	ds_read_b128 v[208:211], v149 offset:36864
	ds_read_b128 v[212:215], v149 offset:37888
	ds_read_b128 v[216:219], v149 offset:38912
	ds_read_b128 v[220:223], v149 offset:39936
	global_load_lds_dwordx4 v130, s[52:53]
	s_mov_b32 m0, s57
	s_nop 0
	global_load_lds_dwordx4 v132, s[52:53]
	s_waitcnt vmcnt(8)
	s_waitcnt lgkmcnt(0)
	s_barrier
	s_setprio 1
	s_waitcnt lgkmcnt(0)
	v_mfma_f32_16x16x32_bf16 v[126:129], v[150:153], v[182:185], v[126:129]
	v_mfma_f32_16x16x32_bf16 v[122:125], v[158:161], v[182:185], v[122:125]
	v_mfma_f32_16x16x32_bf16 v[114:117], v[150:153], v[190:193], v[114:117]
	v_mfma_f32_16x16x32_bf16 v[106:109], v[158:161], v[190:193], v[106:109]
	v_mfma_f32_16x16x32_bf16 v[98:101], v[150:153], v[208:211], v[98:101]
	v_mfma_f32_16x16x32_bf16 v[90:93], v[158:161], v[208:211], v[90:93]
	v_mfma_f32_16x16x32_bf16 v[82:85], v[150:153], v[216:219], v[82:85]
	v_mfma_f32_16x16x32_bf16 v[74:77], v[158:161], v[216:219], v[74:77]
	v_mfma_f32_16x16x32_bf16 v[126:129], v[154:157], v[186:189], v[126:129]
	v_mfma_f32_16x16x32_bf16 v[122:125], v[162:165], v[186:189], v[122:125]
	v_mfma_f32_16x16x32_bf16 v[114:117], v[154:157], v[204:207], v[114:117]
	v_mfma_f32_16x16x32_bf16 v[106:109], v[162:165], v[204:207], v[106:109]
	v_mfma_f32_16x16x32_bf16 v[98:101], v[154:157], v[212:215], v[98:101]
	v_mfma_f32_16x16x32_bf16 v[90:93], v[162:165], v[212:215], v[90:93]
	v_mfma_f32_16x16x32_bf16 v[82:85], v[154:157], v[220:223], v[82:85]
	v_mfma_f32_16x16x32_bf16 v[74:77], v[162:165], v[220:223], v[74:77]
	s_setprio 0
	s_setprio 1
	v_mfma_f32_16x16x32_bf16 v[118:121], v[166:169], v[182:185], v[118:121]
	v_mfma_f32_16x16x32_bf16 v[110:113], v[174:177], v[182:185], v[110:113]
	v_mfma_f32_16x16x32_bf16 v[102:105], v[166:169], v[190:193], v[102:105]
	v_mfma_f32_16x16x32_bf16 v[94:97], v[174:177], v[190:193], v[94:97]
	v_mfma_f32_16x16x32_bf16 v[86:89], v[166:169], v[208:211], v[86:89]
	v_mfma_f32_16x16x32_bf16 v[78:81], v[174:177], v[208:211], v[78:81]
	v_mfma_f32_16x16x32_bf16 v[70:73], v[166:169], v[216:219], v[70:73]
	v_mfma_f32_16x16x32_bf16 v[66:69], v[174:177], v[216:219], v[66:69]
	v_mfma_f32_16x16x32_bf16 v[118:121], v[170:173], v[186:189], v[118:121]
	v_mfma_f32_16x16x32_bf16 v[110:113], v[178:181], v[186:189], v[110:113]
	v_mfma_f32_16x16x32_bf16 v[102:105], v[170:173], v[204:207], v[102:105]
	v_mfma_f32_16x16x32_bf16 v[94:97], v[178:181], v[204:207], v[94:97]
	v_mfma_f32_16x16x32_bf16 v[86:89], v[170:173], v[212:215], v[86:89]
	v_mfma_f32_16x16x32_bf16 v[78:81], v[178:181], v[212:215], v[78:81]
	v_mfma_f32_16x16x32_bf16 v[70:73], v[170:173], v[220:223], v[70:73]
	v_mfma_f32_16x16x32_bf16 v[66:69], v[178:181], v[220:223], v[66:69]
	s_setprio 0
	s_barrier
	s_add_u32 s100, s52, 0xfff80080
	s_addc_u32 s101, s53, -1
	s_add_u32 s98, s50, 0x80
	s_addc_u32 s99, s51, 0
	s_add_i32 s52, s70, s55
	s_mov_b32 m0, s52
	ds_read_b128 v[182:185], v149 offset:49152
	ds_read_b128 v[186:189], v149 offset:50176
	ds_read_b128 v[190:193], v149 offset:51200
	ds_read_b128 v[204:207], v149 offset:52224
	ds_read_b128 v[208:211], v149 offset:53248
	ds_read_b128 v[212:215], v149 offset:54272
	ds_read_b128 v[216:219], v149 offset:55296
	ds_read_b128 v[220:223], v149 offset:56320
	global_load_lds_dwordx4 v0, s[98:99]
	s_add_i32 m0, s52, 0x2000
	s_add_u32 s50, s50, 0x80080
	s_addc_u32 s51, s51, 0
	s_add_i32 s52, s71, s55
	global_load_lds_dwordx4 v134, s[98:99]
	s_mov_b32 m0, s52
	s_nop 0
	global_load_lds_dwordx4 v0, s[50:51]
	s_add_i32 m0, s52, 0x2000
	s_nop 0
	global_load_lds_dwordx4 v134, s[50:51]
	s_mov_b32 m0, s61
	s_nop 0
	global_load_lds_dwordx4 v130, s[100:101]
	s_mov_b32 m0, s62
	s_nop 0
	global_load_lds_dwordx4 v132, s[100:101]
	s_waitcnt vmcnt(8)
	s_waitcnt lgkmcnt(0)
	s_barrier
	s_setprio 1
	s_waitcnt lgkmcnt(0)
	v_mfma_f32_16x16x32_bf16 v[62:65], v[150:153], v[182:185], v[62:65]
	v_mfma_f32_16x16x32_bf16 v[58:61], v[158:161], v[182:185], v[58:61]
	v_mfma_f32_16x16x32_bf16 v[50:53], v[150:153], v[190:193], v[50:53]
	v_mfma_f32_16x16x32_bf16 v[42:45], v[158:161], v[190:193], v[42:45]
	v_mfma_f32_16x16x32_bf16 v[34:37], v[150:153], v[208:211], v[34:37]
	v_mfma_f32_16x16x32_bf16 v[26:29], v[158:161], v[208:211], v[26:29]
	v_mfma_f32_16x16x32_bf16 v[18:21], v[150:153], v[216:219], v[18:21]
	v_mfma_f32_16x16x32_bf16 v[10:13], v[158:161], v[216:219], v[10:13]
	v_mfma_f32_16x16x32_bf16 v[62:65], v[154:157], v[186:189], v[62:65]
	v_mfma_f32_16x16x32_bf16 v[58:61], v[162:165], v[186:189], v[58:61]
	v_mfma_f32_16x16x32_bf16 v[50:53], v[154:157], v[204:207], v[50:53]
	v_mfma_f32_16x16x32_bf16 v[42:45], v[162:165], v[204:207], v[42:45]
	v_mfma_f32_16x16x32_bf16 v[34:37], v[154:157], v[212:215], v[34:37]
	v_mfma_f32_16x16x32_bf16 v[26:29], v[162:165], v[212:215], v[26:29]
	v_mfma_f32_16x16x32_bf16 v[18:21], v[154:157], v[220:223], v[18:21]
	v_mfma_f32_16x16x32_bf16 v[10:13], v[162:165], v[220:223], v[10:13]
	s_setprio 0
	s_setprio 1
	v_mfma_f32_16x16x32_bf16 v[54:57], v[166:169], v[182:185], v[54:57]
	v_mfma_f32_16x16x32_bf16 v[46:49], v[174:177], v[182:185], v[46:49]
	v_mfma_f32_16x16x32_bf16 v[38:41], v[166:169], v[190:193], v[38:41]
	v_mfma_f32_16x16x32_bf16 v[30:33], v[174:177], v[190:193], v[30:33]
	v_mfma_f32_16x16x32_bf16 v[22:25], v[166:169], v[208:211], v[22:25]
	v_mfma_f32_16x16x32_bf16 v[14:17], v[174:177], v[208:211], v[14:17]
	v_mfma_f32_16x16x32_bf16 v[6:9], v[166:169], v[216:219], v[6:9]
	v_mfma_f32_16x16x32_bf16 v[2:5], v[174:177], v[216:219], v[2:5]
	v_mfma_f32_16x16x32_bf16 v[54:57], v[170:173], v[186:189], v[54:57]
	v_mfma_f32_16x16x32_bf16 v[46:49], v[178:181], v[186:189], v[46:49]
	v_mfma_f32_16x16x32_bf16 v[38:41], v[170:173], v[204:207], v[38:41]
	v_mfma_f32_16x16x32_bf16 v[30:33], v[178:181], v[204:207], v[30:33]
	v_mfma_f32_16x16x32_bf16 v[22:25], v[170:173], v[212:215], v[22:25]
	v_mfma_f32_16x16x32_bf16 v[14:17], v[178:181], v[212:215], v[14:17]
	v_mfma_f32_16x16x32_bf16 v[6:9], v[170:173], v[220:223], v[6:9]
	v_mfma_f32_16x16x32_bf16 v[2:5], v[178:181], v[220:223], v[2:5]
	s_setprio 0
	s_barrier
	s_add_u32 s42, s42, 0x100
	s_addc_u32 s43, s43, 0
	s_add_u32 s45, s45, 0x100
	s_addc_u32 s58, s58, 0
	s_cmp_ge_u32 s59, s33
	s_mov_b32 s50, s59
	s_cbranch_scc0 .LBB0_201
	s_branch .Lpeel_exit_0

.Lpeel_exit_0:
	s_and_b64 vcc, exec, s[20:21]
	s_cbranch_vccz .LBB0_206
	s_barrier
	s_cmp_ge_i32 s30, s17
	s_mov_b64 s[42:43], -1
	s_cbranch_scc1 .LBB0_207

.LBB0_344:
	s_ashr_i32 s13, s12, 31
	s_lshl_b64 s[14:15], s[12:13], 18
	s_add_u32 s14, s17, s14
	s_addc_u32 s15, s18, s15
	s_and_b64 s[20:21], s[4:5], exec
	s_cselect_b32 s13, s15, s25
	s_cselect_b32 s40, s14, s24
	s_ashr_i32 s11, s10, 31
	s_lshl_b64 s[20:21], s[10:11], 18
	s_add_u32 s20, s19, s20
	s_addc_u32 s21, s28, s21
	s_and_b64 s[30:31], s[4:5], exec
	s_cselect_b32 s11, s21, s27
	s_cselect_b32 s41, s20, s26
	s_add_u32 s24, s24, 0x20080
	s_addc_u32 s25, s25, 0
	s_add_u32 s43, s26, 0x100
	s_addc_u32 s44, s27, 0
	s_mov_b32 s45, -2
	v_add_u32_e32 v253, 0x10000, v154
	s_add_u32 s26, s24, 0xfffe0080
	s_addc_u32 s27, s25, -1
	s_add_i32 s46, 0, 0x10000
	s_cmp_eq_u32 s45, 4
	s_cselect_b32 s31, s13, s27
	s_cselect_b32 s30, s40, s26
	s_cselect_b32 s27, s11, s44
	s_cselect_b32 s26, s41, s43
	s_add_i32 s52, 0, 0x14000
	ds_read_b128 v[158:161], v253
	ds_read_b128 v[162:165], v253 offset:1024
	ds_read_b128 v[166:169], v253 offset:2048
	ds_read_b128 v[170:173], v253 offset:3072
	ds_read_b128 v[174:177], v253 offset:16384
	ds_read_b128 v[178:181], v253 offset:17408
	ds_read_b128 v[182:185], v253 offset:18432
	ds_read_b128 v[186:189], v253 offset:19456
	s_add_i32 m0, s23, 0xc000
	ds_read_b128 v[190:193], v156
	ds_read_b128 v[204:207], v156 offset:1024
	ds_read_b128 v[208:211], v156 offset:2048
	ds_read_b128 v[212:215], v156 offset:3072
	ds_read_b128 v[216:219], v156 offset:4096
	ds_read_b128 v[220:223], v156 offset:5120
	ds_read_b128 v[224:227], v156 offset:6144
	ds_read_b128 v[228:231], v156 offset:7168
	global_load_lds_dwordx4 v136, s[24:25]
	s_add_i32 m0, s23, 0xe000
	s_nop 0
	global_load_lds_dwordx4 v138, s[24:25]
	s_waitcnt vmcnt(8)
	s_waitcnt lgkmcnt(0)
	s_barrier
	s_setprio 1
	s_waitcnt lgkmcnt(0)
	v_mfma_f32_16x16x32_bf16 v[126:129], v[158:161], v[190:193], 0
	v_mfma_f32_16x16x32_bf16 v[122:125], v[166:169], v[190:193], 0
	v_mfma_f32_16x16x32_bf16 v[114:117], v[158:161], v[208:211], 0
	v_mfma_f32_16x16x32_bf16 v[106:109], v[166:169], v[208:211], 0
	v_mfma_f32_16x16x32_bf16 v[98:101], v[158:161], v[216:219], 0
	v_mfma_f32_16x16x32_bf16 v[90:93], v[166:169], v[216:219], 0
	v_mfma_f32_16x16x32_bf16 v[82:85], v[158:161], v[224:227], 0
	v_mfma_f32_16x16x32_bf16 v[74:77], v[166:169], v[224:227], 0
	v_mfma_f32_16x16x32_bf16 v[126:129], v[162:165], v[204:207], v[126:129]
	v_mfma_f32_16x16x32_bf16 v[122:125], v[170:173], v[204:207], v[122:125]
	v_mfma_f32_16x16x32_bf16 v[114:117], v[162:165], v[212:215], v[114:117]
	v_mfma_f32_16x16x32_bf16 v[106:109], v[170:173], v[212:215], v[106:109]
	v_mfma_f32_16x16x32_bf16 v[98:101], v[162:165], v[220:223], v[98:101]
	v_mfma_f32_16x16x32_bf16 v[90:93], v[170:173], v[220:223], v[90:93]
	v_mfma_f32_16x16x32_bf16 v[82:85], v[162:165], v[228:231], v[82:85]
	v_mfma_f32_16x16x32_bf16 v[74:77], v[170:173], v[228:231], v[74:77]
	s_setprio 0
	s_setprio 1
	v_mfma_f32_16x16x32_bf16 v[118:121], v[174:177], v[190:193], 0
	v_mfma_f32_16x16x32_bf16 v[110:113], v[182:185], v[190:193], 0
	v_mfma_f32_16x16x32_bf16 v[102:105], v[174:177], v[208:211], 0
	v_mfma_f32_16x16x32_bf16 v[94:97], v[182:185], v[208:211], 0
	v_mfma_f32_16x16x32_bf16 v[86:89], v[174:177], v[216:219], 0
	v_mfma_f32_16x16x32_bf16 v[78:81], v[182:185], v[216:219], 0
	v_mfma_f32_16x16x32_bf16 v[70:73], v[174:177], v[224:227], 0
	v_mfma_f32_16x16x32_bf16 v[66:69], v[182:185], v[224:227], 0
	v_mfma_f32_16x16x32_bf16 v[118:121], v[178:181], v[204:207], v[118:121]
	v_mfma_f32_16x16x32_bf16 v[110:113], v[186:189], v[204:207], v[110:113]
	v_mfma_f32_16x16x32_bf16 v[102:105], v[178:181], v[212:215], v[102:105]
	v_mfma_f32_16x16x32_bf16 v[94:97], v[186:189], v[212:215], v[94:97]
	v_mfma_f32_16x16x32_bf16 v[86:89], v[178:181], v[220:223], v[86:89]
	v_mfma_f32_16x16x32_bf16 v[78:81], v[186:189], v[220:223], v[78:81]
	v_mfma_f32_16x16x32_bf16 v[70:73], v[178:181], v[228:231], v[70:73]
	v_mfma_f32_16x16x32_bf16 v[66:69], v[186:189], v[228:231], v[66:69]
	s_setprio 0
	s_barrier
	s_add_i32 s46, s46, s29
	s_mov_b32 m0, s46
	ds_read_b128 v[190:193], v156 offset:16384
	ds_read_b128 v[204:207], v156 offset:17408
	ds_read_b128 v[208:211], v156 offset:18432
	ds_read_b128 v[212:215], v156 offset:19456
	ds_read_b128 v[216:219], v156 offset:20480
	ds_read_b128 v[220:223], v156 offset:21504
	ds_read_b128 v[224:227], v156 offset:22528
	ds_read_b128 v[228:231], v156 offset:23552
	global_load_lds_dwordx4 v0, s[26:27]
	s_add_i32 m0, s46, 0x2000
	s_add_u32 s50, s26, 0x20000
	s_addc_u32 s51, s27, 0
	s_add_i32 s46, s52, s29
	global_load_lds_dwordx4 v130, s[26:27]
	s_mov_b32 m0, s46
	s_nop 0
	global_load_lds_dwordx4 v0, s[50:51]
	s_add_i32 m0, s46, 0x2000
	s_nop 0
	global_load_lds_dwordx4 v130, s[50:51]
	s_mov_b32 m0, s23
	s_nop 0
	global_load_lds_dwordx4 v134, s[30:31]
	s_mov_b32 m0, s35
	s_nop 0
	global_load_lds_dwordx4 v132, s[30:31]
	s_waitcnt vmcnt(8)
	s_waitcnt lgkmcnt(0)
	s_barrier
	s_setprio 1
	s_waitcnt lgkmcnt(0)
	v_mfma_f32_16x16x32_bf16 v[62:65], v[158:161], v[190:193], 0
	v_mfma_f32_16x16x32_bf16 v[58:61], v[166:169], v[190:193], 0
	v_mfma_f32_16x16x32_bf16 v[50:53], v[158:161], v[208:211], 0
	v_mfma_f32_16x16x32_bf16 v[42:45], v[166:169], v[208:211], 0
	v_mfma_f32_16x16x32_bf16 v[34:37], v[158:161], v[216:219], 0
	v_mfma_f32_16x16x32_bf16 v[26:29], v[166:169], v[216:219], 0
	v_mfma_f32_16x16x32_bf16 v[18:21], v[158:161], v[224:227], 0
	v_mfma_f32_16x16x32_bf16 v[10:13], v[166:169], v[224:227], 0
	v_mfma_f32_16x16x32_bf16 v[62:65], v[162:165], v[204:207], v[62:65]
	v_mfma_f32_16x16x32_bf16 v[58:61], v[170:173], v[204:207], v[58:61]
	v_mfma_f32_16x16x32_bf16 v[50:53], v[162:165], v[212:215], v[50:53]
	v_mfma_f32_16x16x32_bf16 v[42:45], v[170:173], v[212:215], v[42:45]
	v_mfma_f32_16x16x32_bf16 v[34:37], v[162:165], v[220:223], v[34:37]
	v_mfma_f32_16x16x32_bf16 v[26:29], v[170:173], v[220:223], v[26:29]
	v_mfma_f32_16x16x32_bf16 v[18:21], v[162:165], v[228:231], v[18:21]
	v_mfma_f32_16x16x32_bf16 v[10:13], v[170:173], v[228:231], v[10:13]
	s_setprio 0
	s_setprio 1
	v_mfma_f32_16x16x32_bf16 v[54:57], v[174:177], v[190:193], 0
	v_mfma_f32_16x16x32_bf16 v[46:49], v[182:185], v[190:193], 0
	v_mfma_f32_16x16x32_bf16 v[38:41], v[174:177], v[208:211], 0
	v_mfma_f32_16x16x32_bf16 v[30:33], v[182:185], v[208:211], 0
	v_mfma_f32_16x16x32_bf16 v[22:25], v[174:177], v[216:219], 0
	v_mfma_f32_16x16x32_bf16 v[14:17], v[182:185], v[216:219], 0
	v_mfma_f32_16x16x32_bf16 v[6:9], v[174:177], v[224:227], 0
	v_mfma_f32_16x16x32_bf16 v[2:5], v[182:185], v[224:227], 0
	v_mfma_f32_16x16x32_bf16 v[54:57], v[178:181], v[204:207], v[54:57]
	v_mfma_f32_16x16x32_bf16 v[46:49], v[186:189], v[204:207], v[46:49]
	v_mfma_f32_16x16x32_bf16 v[38:41], v[178:181], v[212:215], v[38:41]
	v_mfma_f32_16x16x32_bf16 v[30:33], v[186:189], v[212:215], v[30:33]
	v_mfma_f32_16x16x32_bf16 v[22:25], v[178:181], v[220:223], v[22:25]
	v_mfma_f32_16x16x32_bf16 v[14:17], v[186:189], v[220:223], v[14:17]
	v_mfma_f32_16x16x32_bf16 v[6:9], v[178:181], v[228:231], v[6:9]
	v_mfma_f32_16x16x32_bf16 v[2:5], v[186:189], v[228:231], v[2:5]
	s_setprio 0
	s_barrier
	s_add_i32 s46, 0, 0x18000
	s_add_i32 s50, 0, 0x1c000
	ds_read_b128 v[158:161], v253 offset:32768
	ds_read_b128 v[162:165], v253 offset:33792
	ds_read_b128 v[166:169], v253 offset:34816
	ds_read_b128 v[170:173], v253 offset:35840
	ds_read_b128 v[174:177], v253 offset:49152
	ds_read_b128 v[178:181], v253 offset:50176
	ds_read_b128 v[182:185], v253 offset:51200
	ds_read_b128 v[186:189], v253 offset:52224
	s_add_u32 s30, s30, 0x20000
	s_addc_u32 s31, s31, 0
	s_mov_b32 m0, s36
	ds_read_b128 v[190:193], v156 offset:32768
	ds_read_b128 v[204:207], v156 offset:33792
	ds_read_b128 v[208:211], v156 offset:34816
	ds_read_b128 v[212:215], v156 offset:35840
	ds_read_b128 v[216:219], v156 offset:36864
	ds_read_b128 v[220:223], v156 offset:37888
	ds_read_b128 v[224:227], v156 offset:38912
	ds_read_b128 v[228:231], v156 offset:39936
	global_load_lds_dwordx4 v134, s[30:31]
	s_mov_b32 m0, s37
	s_nop 0
	global_load_lds_dwordx4 v132, s[30:31]
	s_waitcnt vmcnt(8)
	s_waitcnt lgkmcnt(0)
	s_barrier
	s_setprio 1
	s_waitcnt lgkmcnt(0)
	v_mfma_f32_16x16x32_bf16 v[126:129], v[158:161], v[190:193], v[126:129]
	v_mfma_f32_16x16x32_bf16 v[122:125], v[166:169], v[190:193], v[122:125]
	v_mfma_f32_16x16x32_bf16 v[114:117], v[158:161], v[208:211], v[114:117]
	v_mfma_f32_16x16x32_bf16 v[106:109], v[166:169], v[208:211], v[106:109]
	v_mfma_f32_16x16x32_bf16 v[98:101], v[158:161], v[216:219], v[98:101]
	v_mfma_f32_16x16x32_bf16 v[90:93], v[166:169], v[216:219], v[90:93]
	v_mfma_f32_16x16x32_bf16 v[82:85], v[158:161], v[224:227], v[82:85]
	v_mfma_f32_16x16x32_bf16 v[74:77], v[166:169], v[224:227], v[74:77]
	v_mfma_f32_16x16x32_bf16 v[126:129], v[162:165], v[204:207], v[126:129]
	v_mfma_f32_16x16x32_bf16 v[122:125], v[170:173], v[204:207], v[122:125]
	v_mfma_f32_16x16x32_bf16 v[114:117], v[162:165], v[212:215], v[114:117]
	v_mfma_f32_16x16x32_bf16 v[106:109], v[170:173], v[212:215], v[106:109]
	v_mfma_f32_16x16x32_bf16 v[98:101], v[162:165], v[220:223], v[98:101]
	v_mfma_f32_16x16x32_bf16 v[90:93], v[170:173], v[220:223], v[90:93]
	v_mfma_f32_16x16x32_bf16 v[82:85], v[162:165], v[228:231], v[82:85]
	v_mfma_f32_16x16x32_bf16 v[74:77], v[170:173], v[228:231], v[74:77]
	s_setprio 0
	s_setprio 1
	v_mfma_f32_16x16x32_bf16 v[118:121], v[174:177], v[190:193], v[118:121]
	v_mfma_f32_16x16x32_bf16 v[110:113], v[182:185], v[190:193], v[110:113]
	v_mfma_f32_16x16x32_bf16 v[102:105], v[174:177], v[208:211], v[102:105]
	v_mfma_f32_16x16x32_bf16 v[94:97], v[182:185], v[208:211], v[94:97]
	v_mfma_f32_16x16x32_bf16 v[86:89], v[174:177], v[216:219], v[86:89]
	v_mfma_f32_16x16x32_bf16 v[78:81], v[182:185], v[216:219], v[78:81]
	v_mfma_f32_16x16x32_bf16 v[70:73], v[174:177], v[224:227], v[70:73]
	v_mfma_f32_16x16x32_bf16 v[66:69], v[182:185], v[224:227], v[66:69]
	v_mfma_f32_16x16x32_bf16 v[118:121], v[178:181], v[204:207], v[118:121]
	v_mfma_f32_16x16x32_bf16 v[110:113], v[186:189], v[204:207], v[110:113]
	v_mfma_f32_16x16x32_bf16 v[102:105], v[178:181], v[212:215], v[102:105]
	v_mfma_f32_16x16x32_bf16 v[94:97], v[186:189], v[212:215], v[94:97]
	v_mfma_f32_16x16x32_bf16 v[86:89], v[178:181], v[220:223], v[86:89]
	v_mfma_f32_16x16x32_bf16 v[78:81], v[186:189], v[220:223], v[78:81]
	v_mfma_f32_16x16x32_bf16 v[70:73], v[178:181], v[228:231], v[70:73]
	v_mfma_f32_16x16x32_bf16 v[66:69], v[186:189], v[228:231], v[66:69]
	s_setprio 0
	s_barrier
	s_add_u32 s100, s30, 0xfffe0080
	s_addc_u32 s101, s31, -1
	s_add_u32 s98, s26, 0x80
	s_addc_u32 s99, s27, 0
	s_add_i32 s30, s46, s29
	s_mov_b32 m0, s30
	ds_read_b128 v[190:193], v156 offset:49152
	ds_read_b128 v[204:207], v156 offset:50176
	ds_read_b128 v[208:211], v156 offset:51200
	ds_read_b128 v[212:215], v156 offset:52224
	ds_read_b128 v[216:219], v156 offset:53248
	ds_read_b128 v[220:223], v156 offset:54272
	ds_read_b128 v[224:227], v156 offset:55296
	ds_read_b128 v[228:231], v156 offset:56320
	global_load_lds_dwordx4 v0, s[98:99]
	s_add_i32 m0, s30, 0x2000
	s_add_u32 s26, s26, 0x20080
	s_addc_u32 s27, s27, 0
	s_add_i32 s30, s50, s29
	global_load_lds_dwordx4 v130, s[98:99]
	s_mov_b32 m0, s30
	s_nop 0
	global_load_lds_dwordx4 v0, s[26:27]
	s_add_i32 m0, s30, 0x2000
	s_nop 0
	global_load_lds_dwordx4 v130, s[26:27]
	s_mov_b32 m0, s38
	s_nop 0
	global_load_lds_dwordx4 v134, s[100:101]
	s_mov_b32 m0, s39
	s_nop 0
	global_load_lds_dwordx4 v132, s[100:101]
	s_waitcnt vmcnt(8)
	s_waitcnt lgkmcnt(0)
	s_barrier
	s_setprio 1
	s_waitcnt lgkmcnt(0)
	v_mfma_f32_16x16x32_bf16 v[62:65], v[158:161], v[190:193], v[62:65]
	v_mfma_f32_16x16x32_bf16 v[58:61], v[166:169], v[190:193], v[58:61]
	v_mfma_f32_16x16x32_bf16 v[50:53], v[158:161], v[208:211], v[50:53]
	v_mfma_f32_16x16x32_bf16 v[42:45], v[166:169], v[208:211], v[42:45]
	v_mfma_f32_16x16x32_bf16 v[34:37], v[158:161], v[216:219], v[34:37]
	v_mfma_f32_16x16x32_bf16 v[26:29], v[166:169], v[216:219], v[26:29]
	v_mfma_f32_16x16x32_bf16 v[18:21], v[158:161], v[224:227], v[18:21]
	v_mfma_f32_16x16x32_bf16 v[10:13], v[166:169], v[224:227], v[10:13]
	v_mfma_f32_16x16x32_bf16 v[62:65], v[162:165], v[204:207], v[62:65]
	v_mfma_f32_16x16x32_bf16 v[58:61], v[170:173], v[204:207], v[58:61]
	v_mfma_f32_16x16x32_bf16 v[50:53], v[162:165], v[212:215], v[50:53]
	v_mfma_f32_16x16x32_bf16 v[42:45], v[170:173], v[212:215], v[42:45]
	v_mfma_f32_16x16x32_bf16 v[34:37], v[162:165], v[220:223], v[34:37]
	v_mfma_f32_16x16x32_bf16 v[26:29], v[170:173], v[220:223], v[26:29]
	v_mfma_f32_16x16x32_bf16 v[18:21], v[162:165], v[228:231], v[18:21]
	v_mfma_f32_16x16x32_bf16 v[10:13], v[170:173], v[228:231], v[10:13]
	s_setprio 0
	s_setprio 1
	v_mfma_f32_16x16x32_bf16 v[54:57], v[174:177], v[190:193], v[54:57]
	v_mfma_f32_16x16x32_bf16 v[46:49], v[182:185], v[190:193], v[46:49]
	v_mfma_f32_16x16x32_bf16 v[38:41], v[174:177], v[208:211], v[38:41]
	v_mfma_f32_16x16x32_bf16 v[30:33], v[182:185], v[208:211], v[30:33]
	v_mfma_f32_16x16x32_bf16 v[22:25], v[174:177], v[216:219], v[22:25]
	v_mfma_f32_16x16x32_bf16 v[14:17], v[182:185], v[216:219], v[14:17]
	v_mfma_f32_16x16x32_bf16 v[6:9], v[174:177], v[224:227], v[6:9]
	v_mfma_f32_16x16x32_bf16 v[2:5], v[182:185], v[224:227], v[2:5]
	v_mfma_f32_16x16x32_bf16 v[54:57], v[178:181], v[204:207], v[54:57]
	v_mfma_f32_16x16x32_bf16 v[46:49], v[186:189], v[204:207], v[46:49]
	v_mfma_f32_16x16x32_bf16 v[38:41], v[178:181], v[212:215], v[38:41]
	v_mfma_f32_16x16x32_bf16 v[30:33], v[186:189], v[212:215], v[30:33]
	v_mfma_f32_16x16x32_bf16 v[22:25], v[178:181], v[220:223], v[22:25]
	v_mfma_f32_16x16x32_bf16 v[14:17], v[186:189], v[220:223], v[14:17]
	v_mfma_f32_16x16x32_bf16 v[6:9], v[178:181], v[228:231], v[6:9]
	v_mfma_f32_16x16x32_bf16 v[2:5], v[186:189], v[228:231], v[2:5]
	s_setprio 0
	s_barrier
	s_add_i32 s45, s45, 2
	s_add_u32 s24, s24, 0x100
	s_addc_u32 s25, s25, 0
	s_add_u32 s43, s43, 0x100
	s_addc_u32 s44, s44, 0
	s_cmp_gt_u32 s45, 5
	s_cbranch_scc0 .LBB0_345
	s_branch .Lpeel_exit_1

.Lpeel_exit_1:
	s_and_b64 vcc, exec, s[8:9]
	s_cbranch_vccz .LBB0_348
	s_barrier

.LBB0_360:
	s_ashr_i32 s11, s10, 31
	s_lshl_b64 s[12:13], s[10:11], 17
	s_add_u32 s12, s28, s12
	s_addc_u32 s13, s29, s13
	s_and_b64 s[14:15], s[4:5], exec
	s_cselect_b32 s11, s13, s25
	s_cselect_b32 s40, s12, s24
	s_ashr_i32 s9, s8, 31
	s_lshl_b64 s[14:15], s[8:9], 17
	s_add_u32 s14, s17, s14
	s_addc_u32 s15, s18, s15
	s_and_b64 s[26:27], s[4:5], exec
	s_cselect_b32 s9, s15, s23
	s_cselect_b32 s41, s14, s22
	s_mov_b32 s36, 0
	s_mov_b64 s[26:27], -1
	s_mov_b64 s[30:31], 0
	v_add_u32_e32 v253, 0x10000, v139
	s_add_u32 s37, s24, s36
	s_addc_u32 s44, s25, 0
	s_add_u32 s42, s37, 0x100
	s_addc_u32 s43, s44, 0
	s_and_b64 s[38:39], s[30:31], exec
	s_cselect_b32 s39, s11, s43
	s_cselect_b32 s38, s40, s42
	s_add_u32 s36, s22, s36
	s_addc_u32 s42, s23, 0
	s_add_u32 s36, s36, 0x100
	s_addc_u32 s42, s42, 0
	s_add_i32 s64, 0, 0x10000
	s_and_b64 s[30:31], s[30:31], exec
	s_cselect_b32 s43, s9, s42
	s_cselect_b32 s42, s41, s36
	s_add_i32 s31, 0, 0x14000
	s_add_u32 s52, s37, 0x10080
	s_addc_u32 s53, s44, 0
	s_add_i32 s63, s64, s19
	s_add_i32 m0, s21, 0xc000
	s_add_i32 s66, s21, 0xe000
	s_add_i32 s60, s63, 0x2000
	s_add_u32 s50, s42, 0x10000
	ds_read_b128 v[144:147], v253
	ds_read_b128 v[148:151], v253 offset:1024
	ds_read_b128 v[152:155], v253 offset:2048
	ds_read_b128 v[156:159], v253 offset:3072
	s_addc_u32 s51, s43, 0
	s_add_i32 s62, s31, s19
	ds_read_b128 v[160:163], v253 offset:16384
	ds_read_b128 v[164:167], v253 offset:17408
	ds_read_b128 v[168:171], v253 offset:18432
	ds_read_b128 v[172:175], v253 offset:19456
	s_add_i32 s61, s62, 0x2000
	s_add_i32 s59, 0, 0x18000
	s_add_i32 s58, 0, 0x1c000
	s_add_u32 s36, s38, 0x10000
	s_addc_u32 s37, s39, 0
	s_add_i32 s45, s59, s19
	s_add_i32 s44, s45, 0x2000
	s_add_u32 s30, s42, 0x10080
	s_addc_u32 s31, s43, 0
	s_add_i32 s65, s58, s19
	s_add_i32 s64, s65, 0x2000
	ds_read_b128 v[176:179], v141
	ds_read_b128 v[180:183], v141 offset:1024
	ds_read_b128 v[184:187], v141 offset:2048
	ds_read_b128 v[188:191], v141 offset:3072
	ds_read_b128 v[204:207], v141 offset:4096
	ds_read_b128 v[208:211], v141 offset:5120
	ds_read_b128 v[212:215], v141 offset:6144
	ds_read_b128 v[216:219], v141 offset:7168
	global_load_lds_dwordx4 v134, s[52:53]
	s_mov_b32 m0, s66
	s_nop 0
	global_load_lds_dwordx4 v132, s[52:53]
	s_waitcnt vmcnt(8)
	s_waitcnt lgkmcnt(0)
	s_barrier
	s_setprio 1
	s_waitcnt lgkmcnt(0)
	v_mfma_f32_16x16x32_bf16 v[126:129], v[144:147], v[176:179], 0
	v_mfma_f32_16x16x32_bf16 v[122:125], v[152:155], v[176:179], 0
	v_mfma_f32_16x16x32_bf16 v[114:117], v[144:147], v[184:187], 0
	v_mfma_f32_16x16x32_bf16 v[106:109], v[152:155], v[184:187], 0
	v_mfma_f32_16x16x32_bf16 v[98:101], v[144:147], v[204:207], 0
	v_mfma_f32_16x16x32_bf16 v[90:93], v[152:155], v[204:207], 0
	v_mfma_f32_16x16x32_bf16 v[82:85], v[144:147], v[212:215], 0
	v_mfma_f32_16x16x32_bf16 v[74:77], v[152:155], v[212:215], 0
	v_mfma_f32_16x16x32_bf16 v[126:129], v[148:151], v[180:183], v[126:129]
	v_mfma_f32_16x16x32_bf16 v[122:125], v[156:159], v[180:183], v[122:125]
	v_mfma_f32_16x16x32_bf16 v[114:117], v[148:151], v[188:191], v[114:117]
	v_mfma_f32_16x16x32_bf16 v[106:109], v[156:159], v[188:191], v[106:109]
	v_mfma_f32_16x16x32_bf16 v[98:101], v[148:151], v[208:211], v[98:101]
	v_mfma_f32_16x16x32_bf16 v[90:93], v[156:159], v[208:211], v[90:93]
	v_mfma_f32_16x16x32_bf16 v[82:85], v[148:151], v[216:219], v[82:85]
	v_mfma_f32_16x16x32_bf16 v[74:77], v[156:159], v[216:219], v[74:77]
	s_setprio 0
	s_setprio 1
	v_mfma_f32_16x16x32_bf16 v[118:121], v[160:163], v[176:179], 0
	v_mfma_f32_16x16x32_bf16 v[110:113], v[168:171], v[176:179], 0
	v_mfma_f32_16x16x32_bf16 v[102:105], v[160:163], v[184:187], 0
	v_mfma_f32_16x16x32_bf16 v[94:97], v[168:171], v[184:187], 0
	v_mfma_f32_16x16x32_bf16 v[86:89], v[160:163], v[204:207], 0
	v_mfma_f32_16x16x32_bf16 v[78:81], v[168:171], v[204:207], 0
	v_mfma_f32_16x16x32_bf16 v[70:73], v[160:163], v[212:215], 0
	v_mfma_f32_16x16x32_bf16 v[66:69], v[168:171], v[212:215], 0
	v_mfma_f32_16x16x32_bf16 v[118:121], v[164:167], v[180:183], v[118:121]
	v_mfma_f32_16x16x32_bf16 v[110:113], v[172:175], v[180:183], v[110:113]
	v_mfma_f32_16x16x32_bf16 v[102:105], v[164:167], v[188:191], v[102:105]
	v_mfma_f32_16x16x32_bf16 v[94:97], v[172:175], v[188:191], v[94:97]
	v_mfma_f32_16x16x32_bf16 v[86:89], v[164:167], v[208:211], v[86:89]
	v_mfma_f32_16x16x32_bf16 v[78:81], v[172:175], v[208:211], v[78:81]
	v_mfma_f32_16x16x32_bf16 v[70:73], v[164:167], v[216:219], v[70:73]
	v_mfma_f32_16x16x32_bf16 v[66:69], v[172:175], v[216:219], v[66:69]
	s_setprio 0
	s_barrier
	s_mov_b32 m0, s63
	ds_read_b128 v[176:179], v141 offset:16384
	ds_read_b128 v[180:183], v141 offset:17408
	ds_read_b128 v[184:187], v141 offset:18432
	ds_read_b128 v[188:191], v141 offset:19456
	ds_read_b128 v[204:207], v141 offset:20480
	ds_read_b128 v[208:211], v141 offset:21504
	ds_read_b128 v[212:215], v141 offset:22528
	ds_read_b128 v[216:219], v141 offset:23552
	global_load_lds_dwordx4 v0, s[42:43]
	s_mov_b32 m0, s60
	s_nop 0
	global_load_lds_dwordx4 v130, s[42:43]
	s_mov_b32 m0, s62
	s_nop 0
	global_load_lds_dwordx4 v0, s[50:51]
	s_mov_b32 m0, s61
	s_nop 0
	global_load_lds_dwordx4 v130, s[50:51]
	s_mov_b32 m0, s21
	s_nop 0
	global_load_lds_dwordx4 v134, s[38:39]
	s_mov_b32 m0, s35
	s_nop 0
	global_load_lds_dwordx4 v132, s[38:39]
	s_waitcnt vmcnt(8)
	s_waitcnt lgkmcnt(0)
	s_barrier
	s_setprio 1
	s_waitcnt lgkmcnt(0)
	v_mfma_f32_16x16x32_bf16 v[62:65], v[144:147], v[176:179], 0
	v_mfma_f32_16x16x32_bf16 v[58:61], v[152:155], v[176:179], 0
	v_mfma_f32_16x16x32_bf16 v[50:53], v[144:147], v[184:187], 0
	v_mfma_f32_16x16x32_bf16 v[42:45], v[152:155], v[184:187], 0
	v_mfma_f32_16x16x32_bf16 v[34:37], v[144:147], v[204:207], 0
	v_mfma_f32_16x16x32_bf16 v[26:29], v[152:155], v[204:207], 0
	v_mfma_f32_16x16x32_bf16 v[18:21], v[144:147], v[212:215], 0
	v_mfma_f32_16x16x32_bf16 v[10:13], v[152:155], v[212:215], 0
	v_mfma_f32_16x16x32_bf16 v[62:65], v[148:151], v[180:183], v[62:65]
	v_mfma_f32_16x16x32_bf16 v[58:61], v[156:159], v[180:183], v[58:61]
	v_mfma_f32_16x16x32_bf16 v[50:53], v[148:151], v[188:191], v[50:53]
	v_mfma_f32_16x16x32_bf16 v[42:45], v[156:159], v[188:191], v[42:45]
	v_mfma_f32_16x16x32_bf16 v[34:37], v[148:151], v[208:211], v[34:37]
	v_mfma_f32_16x16x32_bf16 v[26:29], v[156:159], v[208:211], v[26:29]
	v_mfma_f32_16x16x32_bf16 v[18:21], v[148:151], v[216:219], v[18:21]
	v_mfma_f32_16x16x32_bf16 v[10:13], v[156:159], v[216:219], v[10:13]
	s_setprio 0
	s_setprio 1
	v_mfma_f32_16x16x32_bf16 v[54:57], v[160:163], v[176:179], 0
	v_mfma_f32_16x16x32_bf16 v[46:49], v[168:171], v[176:179], 0
	v_mfma_f32_16x16x32_bf16 v[38:41], v[160:163], v[184:187], 0
	v_mfma_f32_16x16x32_bf16 v[30:33], v[168:171], v[184:187], 0
	v_mfma_f32_16x16x32_bf16 v[22:25], v[160:163], v[204:207], 0
	v_mfma_f32_16x16x32_bf16 v[14:17], v[168:171], v[204:207], 0
	v_mfma_f32_16x16x32_bf16 v[6:9], v[160:163], v[212:215], 0
	v_mfma_f32_16x16x32_bf16 v[2:5], v[168:171], v[212:215], 0
	v_mfma_f32_16x16x32_bf16 v[54:57], v[164:167], v[180:183], v[54:57]
	v_mfma_f32_16x16x32_bf16 v[46:49], v[172:175], v[180:183], v[46:49]
	v_mfma_f32_16x16x32_bf16 v[38:41], v[164:167], v[188:191], v[38:41]
	v_mfma_f32_16x16x32_bf16 v[30:33], v[172:175], v[188:191], v[30:33]
	v_mfma_f32_16x16x32_bf16 v[22:25], v[164:167], v[208:211], v[22:25]
	v_mfma_f32_16x16x32_bf16 v[14:17], v[172:175], v[208:211], v[14:17]
	v_mfma_f32_16x16x32_bf16 v[6:9], v[164:167], v[216:219], v[6:9]
	v_mfma_f32_16x16x32_bf16 v[2:5], v[172:175], v[216:219], v[2:5]
	s_setprio 0
	s_barrier
	ds_read_b128 v[144:147], v253 offset:32768
	ds_read_b128 v[148:151], v253 offset:33792
	ds_read_b128 v[152:155], v253 offset:34816
	ds_read_b128 v[156:159], v253 offset:35840
	ds_read_b128 v[160:163], v253 offset:49152
	ds_read_b128 v[164:167], v253 offset:50176
	ds_read_b128 v[168:171], v253 offset:51200
	ds_read_b128 v[172:175], v253 offset:52224
	s_mov_b32 m0, s46
	ds_read_b128 v[176:179], v141 offset:32768
	ds_read_b128 v[180:183], v141 offset:33792
	ds_read_b128 v[184:187], v141 offset:34816
	ds_read_b128 v[188:191], v141 offset:35840
	ds_read_b128 v[204:207], v141 offset:36864
	ds_read_b128 v[208:211], v141 offset:37888
	ds_read_b128 v[212:215], v141 offset:38912
	ds_read_b128 v[216:219], v141 offset:39936
	global_load_lds_dwordx4 v134, s[36:37]
	s_mov_b32 m0, s54
	s_nop 0
	global_load_lds_dwordx4 v132, s[36:37]
	s_waitcnt vmcnt(8)
	s_waitcnt lgkmcnt(0)
	s_barrier
	s_setprio 1
	s_waitcnt lgkmcnt(0)
	v_mfma_f32_16x16x32_bf16 v[126:129], v[144:147], v[176:179], v[126:129]
	v_mfma_f32_16x16x32_bf16 v[122:125], v[152:155], v[176:179], v[122:125]
	v_mfma_f32_16x16x32_bf16 v[114:117], v[144:147], v[184:187], v[114:117]
	v_mfma_f32_16x16x32_bf16 v[106:109], v[152:155], v[184:187], v[106:109]
	v_mfma_f32_16x16x32_bf16 v[98:101], v[144:147], v[204:207], v[98:101]
	v_mfma_f32_16x16x32_bf16 v[90:93], v[152:155], v[204:207], v[90:93]
	v_mfma_f32_16x16x32_bf16 v[82:85], v[144:147], v[212:215], v[82:85]
	v_mfma_f32_16x16x32_bf16 v[74:77], v[152:155], v[212:215], v[74:77]
	v_mfma_f32_16x16x32_bf16 v[126:129], v[148:151], v[180:183], v[126:129]
	v_mfma_f32_16x16x32_bf16 v[122:125], v[156:159], v[180:183], v[122:125]
	v_mfma_f32_16x16x32_bf16 v[114:117], v[148:151], v[188:191], v[114:117]
	v_mfma_f32_16x16x32_bf16 v[106:109], v[156:159], v[188:191], v[106:109]
	v_mfma_f32_16x16x32_bf16 v[98:101], v[148:151], v[208:211], v[98:101]
	v_mfma_f32_16x16x32_bf16 v[90:93], v[156:159], v[208:211], v[90:93]
	v_mfma_f32_16x16x32_bf16 v[82:85], v[148:151], v[216:219], v[82:85]
	v_mfma_f32_16x16x32_bf16 v[74:77], v[156:159], v[216:219], v[74:77]
	s_setprio 0
	s_setprio 1
	v_mfma_f32_16x16x32_bf16 v[118:121], v[160:163], v[176:179], v[118:121]
	v_mfma_f32_16x16x32_bf16 v[110:113], v[168:171], v[176:179], v[110:113]
	v_mfma_f32_16x16x32_bf16 v[102:105], v[160:163], v[184:187], v[102:105]
	v_mfma_f32_16x16x32_bf16 v[94:97], v[168:171], v[184:187], v[94:97]
	v_mfma_f32_16x16x32_bf16 v[86:89], v[160:163], v[204:207], v[86:89]
	v_mfma_f32_16x16x32_bf16 v[78:81], v[168:171], v[204:207], v[78:81]
	v_mfma_f32_16x16x32_bf16 v[70:73], v[160:163], v[212:215], v[70:73]
	v_mfma_f32_16x16x32_bf16 v[66:69], v[168:171], v[212:215], v[66:69]
	v_mfma_f32_16x16x32_bf16 v[118:121], v[164:167], v[180:183], v[118:121]
	v_mfma_f32_16x16x32_bf16 v[110:113], v[172:175], v[180:183], v[110:113]
	v_mfma_f32_16x16x32_bf16 v[102:105], v[164:167], v[188:191], v[102:105]
	v_mfma_f32_16x16x32_bf16 v[94:97], v[172:175], v[188:191], v[94:97]
	v_mfma_f32_16x16x32_bf16 v[86:89], v[164:167], v[208:211], v[86:89]
	v_mfma_f32_16x16x32_bf16 v[78:81], v[172:175], v[208:211], v[78:81]
	v_mfma_f32_16x16x32_bf16 v[70:73], v[164:167], v[216:219], v[70:73]
	v_mfma_f32_16x16x32_bf16 v[66:69], v[172:175], v[216:219], v[66:69]
	s_setprio 0
	s_barrier
	s_add_u32 s100, s38, 0x80
	s_addc_u32 s101, s39, 0
	s_add_u32 s98, s42, 0x80
	s_addc_u32 s99, s43, 0
	s_mov_b32 m0, s45
	ds_read_b128 v[176:179], v141 offset:49152
	ds_read_b128 v[180:183], v141 offset:50176
	ds_read_b128 v[184:187], v141 offset:51200
	ds_read_b128 v[188:191], v141 offset:52224
	ds_read_b128 v[204:207], v141 offset:53248
	ds_read_b128 v[208:211], v141 offset:54272
	ds_read_b128 v[212:215], v141 offset:55296
	ds_read_b128 v[216:219], v141 offset:56320
	global_load_lds_dwordx4 v0, s[98:99]
	s_mov_b32 m0, s44
	s_nop 0
	global_load_lds_dwordx4 v130, s[98:99]
	s_mov_b32 m0, s65
	s_nop 0
	global_load_lds_dwordx4 v0, s[30:31]
	s_mov_b32 m0, s64
	s_nop 0
	global_load_lds_dwordx4 v130, s[30:31]
	s_mov_b32 m0, s55
	s_nop 0
	global_load_lds_dwordx4 v134, s[100:101]
	s_mov_b32 m0, s56
	s_nop 0
	global_load_lds_dwordx4 v132, s[100:101]
	s_waitcnt vmcnt(8)
	s_waitcnt lgkmcnt(0)
	s_barrier
	s_setprio 1
	s_waitcnt lgkmcnt(0)
	v_mfma_f32_16x16x32_bf16 v[62:65], v[144:147], v[176:179], v[62:65]
	v_mfma_f32_16x16x32_bf16 v[58:61], v[152:155], v[176:179], v[58:61]
	v_mfma_f32_16x16x32_bf16 v[50:53], v[144:147], v[184:187], v[50:53]
	v_mfma_f32_16x16x32_bf16 v[42:45], v[152:155], v[184:187], v[42:45]
	v_mfma_f32_16x16x32_bf16 v[34:37], v[144:147], v[204:207], v[34:37]
	v_mfma_f32_16x16x32_bf16 v[26:29], v[152:155], v[204:207], v[26:29]
	v_mfma_f32_16x16x32_bf16 v[18:21], v[144:147], v[212:215], v[18:21]
	v_mfma_f32_16x16x32_bf16 v[10:13], v[152:155], v[212:215], v[10:13]
	v_mfma_f32_16x16x32_bf16 v[62:65], v[148:151], v[180:183], v[62:65]
	v_mfma_f32_16x16x32_bf16 v[58:61], v[156:159], v[180:183], v[58:61]
	v_mfma_f32_16x16x32_bf16 v[50:53], v[148:151], v[188:191], v[50:53]
	v_mfma_f32_16x16x32_bf16 v[42:45], v[156:159], v[188:191], v[42:45]
	v_mfma_f32_16x16x32_bf16 v[34:37], v[148:151], v[208:211], v[34:37]
	v_mfma_f32_16x16x32_bf16 v[26:29], v[156:159], v[208:211], v[26:29]
	v_mfma_f32_16x16x32_bf16 v[18:21], v[148:151], v[216:219], v[18:21]
	v_mfma_f32_16x16x32_bf16 v[10:13], v[156:159], v[216:219], v[10:13]
	s_setprio 0
	s_setprio 1
	v_mfma_f32_16x16x32_bf16 v[54:57], v[160:163], v[176:179], v[54:57]
	v_mfma_f32_16x16x32_bf16 v[46:49], v[168:171], v[176:179], v[46:49]
	v_mfma_f32_16x16x32_bf16 v[38:41], v[160:163], v[184:187], v[38:41]
	v_mfma_f32_16x16x32_bf16 v[30:33], v[168:171], v[184:187], v[30:33]
	v_mfma_f32_16x16x32_bf16 v[22:25], v[160:163], v[204:207], v[22:25]
	v_mfma_f32_16x16x32_bf16 v[14:17], v[168:171], v[204:207], v[14:17]
	v_mfma_f32_16x16x32_bf16 v[6:9], v[160:163], v[212:215], v[6:9]
	v_mfma_f32_16x16x32_bf16 v[2:5], v[168:171], v[212:215], v[2:5]
	v_mfma_f32_16x16x32_bf16 v[54:57], v[164:167], v[180:183], v[54:57]
	v_mfma_f32_16x16x32_bf16 v[46:49], v[172:175], v[180:183], v[46:49]
	v_mfma_f32_16x16x32_bf16 v[38:41], v[164:167], v[188:191], v[38:41]
	v_mfma_f32_16x16x32_bf16 v[30:33], v[172:175], v[188:191], v[30:33]
	v_mfma_f32_16x16x32_bf16 v[22:25], v[164:167], v[208:211], v[22:25]
	v_mfma_f32_16x16x32_bf16 v[14:17], v[172:175], v[208:211], v[14:17]
	v_mfma_f32_16x16x32_bf16 v[6:9], v[164:167], v[216:219], v[6:9]
	v_mfma_f32_16x16x32_bf16 v[2:5], v[172:175], v[216:219], v[2:5]
	s_setprio 0
	s_barrier
	s_movk_i32 s36, 0x100
	s_andn2_b64 vcc, exec, s[26:27]
	s_mov_b64 s[30:31], -1
	s_mov_b64 s[26:27], 0
	s_cbranch_vccz .LBB0_361
	s_branch .Lpeel_exit_2

.Lpeel_exit_2:
	s_and_b64 vcc, exec, s[6:7]
	s_cbranch_vccz .LBB0_364
	s_barrier

.LBB0_976:
	s_add_i32 s13, s27, -2
	s_add_u32 s38, s38, 0x80080
	s_addc_u32 s39, s39, 0
	s_add_u32 s15, s42, 0x100
	s_addc_u32 s21, s43, 0
	s_mov_b32 s33, 0
	s_waitcnt vmcnt(0)
	v_add_u32_e32 v253, 0x10000, v192
	s_add_i32 s37, s33, 2
	s_add_u32 s40, s38, 0xfff80080
	s_addc_u32 s41, s39, -1
	s_add_i32 s44, 0, 0x10000
	s_cmp_eq_u32 s13, s33
	s_cselect_b32 s51, s23, s41
	s_cselect_b32 s50, s22, s40
	s_cselect_b32 s43, s25, s21
	s_cselect_b32 s42, s24, s15
	s_add_i32 s33, 0, 0x14000
	ds_read_b128 v[122:125], v253
	ds_read_b128 v[126:129], v253 offset:1024
	ds_read_b128 v[130:133], v253 offset:2048
	ds_read_b128 v[134:137], v253 offset:3072
	ds_read_b128 v[146:149], v253 offset:16384
	ds_read_b128 v[150:153], v253 offset:17408
	ds_read_b128 v[154:157], v253 offset:18432
	ds_read_b128 v[158:161], v253 offset:19456
	s_add_i32 m0, s31, 0xc000
	ds_read_b128 v[162:165], v204
	ds_read_b128 v[176:179], v204 offset:1024
	ds_read_b128 v[180:183], v204 offset:2048
	ds_read_b128 v[184:187], v204 offset:3072
	ds_read_b128 v[206:209], v204 offset:4096
	ds_read_b128 v[210:213], v204 offset:5120
	ds_read_b128 v[214:217], v204 offset:6144
	ds_read_b128 v[218:221], v204 offset:7168
	global_load_lds_dwordx4 v172, s[38:39]
	s_add_i32 m0, s31, 0xe000
	s_nop 0
	global_load_lds_dwordx4 v174, s[38:39]
	s_waitcnt vmcnt(8)
	s_waitcnt lgkmcnt(0)
	s_barrier
	s_setprio 1
	s_waitcnt lgkmcnt(0)
	v_mfma_f32_16x16x32_bf16 v[142:145], v[122:125], v[162:165], 0
	v_mfma_f32_16x16x32_bf16 v[138:141], v[130:133], v[162:165], 0
	v_mfma_f32_16x16x32_bf16 v[118:121], v[122:125], v[180:183], 0
	v_mfma_f32_16x16x32_bf16 v[110:113], v[130:133], v[180:183], 0
	v_mfma_f32_16x16x32_bf16 v[98:101], v[122:125], v[206:209], 0
	v_mfma_f32_16x16x32_bf16 v[90:93], v[130:133], v[206:209], 0
	v_mfma_f32_16x16x32_bf16 v[82:85], v[122:125], v[214:217], 0
	v_mfma_f32_16x16x32_bf16 v[74:77], v[130:133], v[214:217], 0
	v_mfma_f32_16x16x32_bf16 v[142:145], v[126:129], v[176:179], v[142:145]
	v_mfma_f32_16x16x32_bf16 v[138:141], v[134:137], v[176:179], v[138:141]
	v_mfma_f32_16x16x32_bf16 v[118:121], v[126:129], v[184:187], v[118:121]
	v_mfma_f32_16x16x32_bf16 v[110:113], v[134:137], v[184:187], v[110:113]
	v_mfma_f32_16x16x32_bf16 v[98:101], v[126:129], v[210:213], v[98:101]
	v_mfma_f32_16x16x32_bf16 v[90:93], v[134:137], v[210:213], v[90:93]
	v_mfma_f32_16x16x32_bf16 v[82:85], v[126:129], v[218:221], v[82:85]
	v_mfma_f32_16x16x32_bf16 v[74:77], v[134:137], v[218:221], v[74:77]
	s_setprio 0
	s_setprio 1
	v_mfma_f32_16x16x32_bf16 v[114:117], v[146:149], v[162:165], 0
	v_mfma_f32_16x16x32_bf16 v[106:109], v[154:157], v[162:165], 0
	v_mfma_f32_16x16x32_bf16 v[102:105], v[146:149], v[180:183], 0
	v_mfma_f32_16x16x32_bf16 v[94:97], v[154:157], v[180:183], 0
	v_mfma_f32_16x16x32_bf16 v[86:89], v[146:149], v[206:209], 0
	v_mfma_f32_16x16x32_bf16 v[78:81], v[154:157], v[206:209], 0
	v_mfma_f32_16x16x32_bf16 v[70:73], v[146:149], v[214:217], 0
	v_mfma_f32_16x16x32_bf16 v[66:69], v[154:157], v[214:217], 0
	v_mfma_f32_16x16x32_bf16 v[114:117], v[150:153], v[176:179], v[114:117]
	v_mfma_f32_16x16x32_bf16 v[106:109], v[158:161], v[176:179], v[106:109]
	v_mfma_f32_16x16x32_bf16 v[102:105], v[150:153], v[184:187], v[102:105]
	v_mfma_f32_16x16x32_bf16 v[94:97], v[158:161], v[184:187], v[94:97]
	v_mfma_f32_16x16x32_bf16 v[86:89], v[150:153], v[210:213], v[86:89]
	v_mfma_f32_16x16x32_bf16 v[78:81], v[158:161], v[210:213], v[78:81]
	v_mfma_f32_16x16x32_bf16 v[70:73], v[150:153], v[218:221], v[70:73]
	v_mfma_f32_16x16x32_bf16 v[66:69], v[158:161], v[218:221], v[66:69]
	s_setprio 0
	s_barrier
	s_add_i32 s40, s44, s19
	s_mov_b32 m0, s40
	ds_read_b128 v[162:165], v204 offset:16384
	ds_read_b128 v[176:179], v204 offset:17408
	ds_read_b128 v[180:183], v204 offset:18432
	ds_read_b128 v[184:187], v204 offset:19456
	ds_read_b128 v[206:209], v204 offset:20480
	ds_read_b128 v[210:213], v204 offset:21504
	ds_read_b128 v[214:217], v204 offset:22528
	ds_read_b128 v[218:221], v204 offset:23552
	global_load_lds_dwordx4 v0, s[42:43]
	s_add_i32 m0, s40, 0x2000
	s_add_u32 s40, s42, 0x80000
	s_addc_u32 s41, s43, 0
	s_add_i32 s33, s33, s19
	global_load_lds_dwordx4 v170, s[42:43]
	s_mov_b32 m0, s33
	s_nop 0
	global_load_lds_dwordx4 v0, s[40:41]
	s_add_i32 m0, s33, 0x2000
	s_nop 0
	global_load_lds_dwordx4 v170, s[40:41]
	s_mov_b32 m0, s31
	s_nop 0
	global_load_lds_dwordx4 v166, s[50:51]
	s_mov_b32 m0, s34
	s_nop 0
	global_load_lds_dwordx4 v168, s[50:51]
	s_waitcnt vmcnt(8)
	s_waitcnt lgkmcnt(0)
	s_barrier
	s_setprio 1
	s_waitcnt lgkmcnt(0)
	v_mfma_f32_16x16x32_bf16 v[62:65], v[122:125], v[162:165], 0
	v_mfma_f32_16x16x32_bf16 v[58:61], v[130:133], v[162:165], 0
	v_mfma_f32_16x16x32_bf16 v[50:53], v[122:125], v[180:183], 0
	v_mfma_f32_16x16x32_bf16 v[42:45], v[130:133], v[180:183], 0
	v_mfma_f32_16x16x32_bf16 v[34:37], v[122:125], v[206:209], 0
	v_mfma_f32_16x16x32_bf16 v[26:29], v[130:133], v[206:209], 0
	v_mfma_f32_16x16x32_bf16 v[18:21], v[122:125], v[214:217], 0
	v_mfma_f32_16x16x32_bf16 v[10:13], v[130:133], v[214:217], 0
	v_mfma_f32_16x16x32_bf16 v[62:65], v[126:129], v[176:179], v[62:65]
	v_mfma_f32_16x16x32_bf16 v[58:61], v[134:137], v[176:179], v[58:61]
	v_mfma_f32_16x16x32_bf16 v[50:53], v[126:129], v[184:187], v[50:53]
	v_mfma_f32_16x16x32_bf16 v[42:45], v[134:137], v[184:187], v[42:45]
	v_mfma_f32_16x16x32_bf16 v[34:37], v[126:129], v[210:213], v[34:37]
	v_mfma_f32_16x16x32_bf16 v[26:29], v[134:137], v[210:213], v[26:29]
	v_mfma_f32_16x16x32_bf16 v[18:21], v[126:129], v[218:221], v[18:21]
	v_mfma_f32_16x16x32_bf16 v[10:13], v[134:137], v[218:221], v[10:13]
	s_setprio 0
	s_setprio 1
	v_mfma_f32_16x16x32_bf16 v[54:57], v[146:149], v[162:165], 0
	v_mfma_f32_16x16x32_bf16 v[46:49], v[154:157], v[162:165], 0
	v_mfma_f32_16x16x32_bf16 v[38:41], v[146:149], v[180:183], 0
	v_mfma_f32_16x16x32_bf16 v[30:33], v[154:157], v[180:183], 0
	v_mfma_f32_16x16x32_bf16 v[22:25], v[146:149], v[206:209], 0
	v_mfma_f32_16x16x32_bf16 v[14:17], v[154:157], v[206:209], 0
	v_mfma_f32_16x16x32_bf16 v[6:9], v[146:149], v[214:217], 0
	v_mfma_f32_16x16x32_bf16 v[2:5], v[154:157], v[214:217], 0
	v_mfma_f32_16x16x32_bf16 v[54:57], v[150:153], v[176:179], v[54:57]
	v_mfma_f32_16x16x32_bf16 v[46:49], v[158:161], v[176:179], v[46:49]
	v_mfma_f32_16x16x32_bf16 v[38:41], v[150:153], v[184:187], v[38:41]
	v_mfma_f32_16x16x32_bf16 v[30:33], v[158:161], v[184:187], v[30:33]
	v_mfma_f32_16x16x32_bf16 v[22:25], v[150:153], v[210:213], v[22:25]
	v_mfma_f32_16x16x32_bf16 v[14:17], v[158:161], v[210:213], v[14:17]
	v_mfma_f32_16x16x32_bf16 v[6:9], v[150:153], v[218:221], v[6:9]
	v_mfma_f32_16x16x32_bf16 v[2:5], v[158:161], v[218:221], v[2:5]
	s_setprio 0
	s_barrier
	s_add_i32 s33, 0, 0x18000
	s_add_i32 s44, 0, 0x1c000
	ds_read_b128 v[122:125], v253 offset:32768
	ds_read_b128 v[126:129], v253 offset:33792
	ds_read_b128 v[130:133], v253 offset:34816
	ds_read_b128 v[134:137], v253 offset:35840
	ds_read_b128 v[146:149], v253 offset:49152
	ds_read_b128 v[150:153], v253 offset:50176
	ds_read_b128 v[154:157], v253 offset:51200
	ds_read_b128 v[158:161], v253 offset:52224
	s_add_u32 s40, s50, 0x80000
	s_addc_u32 s41, s51, 0
	s_mov_b32 m0, s35
	ds_read_b128 v[162:165], v204 offset:32768
	ds_read_b128 v[176:179], v204 offset:33792
	ds_read_b128 v[180:183], v204 offset:34816
	ds_read_b128 v[184:187], v204 offset:35840
	ds_read_b128 v[206:209], v204 offset:36864
	ds_read_b128 v[210:213], v204 offset:37888
	ds_read_b128 v[214:217], v204 offset:38912
	ds_read_b128 v[218:221], v204 offset:39936
	global_load_lds_dwordx4 v166, s[40:41]
	s_mov_b32 m0, s46
	s_nop 0
	global_load_lds_dwordx4 v168, s[40:41]
	s_waitcnt vmcnt(8)
	s_waitcnt lgkmcnt(0)
	s_barrier
	s_setprio 1
	s_waitcnt lgkmcnt(0)
	v_mfma_f32_16x16x32_bf16 v[142:145], v[122:125], v[162:165], v[142:145]
	v_mfma_f32_16x16x32_bf16 v[138:141], v[130:133], v[162:165], v[138:141]
	v_mfma_f32_16x16x32_bf16 v[118:121], v[122:125], v[180:183], v[118:121]
	v_mfma_f32_16x16x32_bf16 v[110:113], v[130:133], v[180:183], v[110:113]
	v_mfma_f32_16x16x32_bf16 v[98:101], v[122:125], v[206:209], v[98:101]
	v_mfma_f32_16x16x32_bf16 v[90:93], v[130:133], v[206:209], v[90:93]
	v_mfma_f32_16x16x32_bf16 v[82:85], v[122:125], v[214:217], v[82:85]
	v_mfma_f32_16x16x32_bf16 v[74:77], v[130:133], v[214:217], v[74:77]
	v_mfma_f32_16x16x32_bf16 v[142:145], v[126:129], v[176:179], v[142:145]
	v_mfma_f32_16x16x32_bf16 v[138:141], v[134:137], v[176:179], v[138:141]
	v_mfma_f32_16x16x32_bf16 v[118:121], v[126:129], v[184:187], v[118:121]
	v_mfma_f32_16x16x32_bf16 v[110:113], v[134:137], v[184:187], v[110:113]
	v_mfma_f32_16x16x32_bf16 v[98:101], v[126:129], v[210:213], v[98:101]
	v_mfma_f32_16x16x32_bf16 v[90:93], v[134:137], v[210:213], v[90:93]
	v_mfma_f32_16x16x32_bf16 v[82:85], v[126:129], v[218:221], v[82:85]
	v_mfma_f32_16x16x32_bf16 v[74:77], v[134:137], v[218:221], v[74:77]
	s_setprio 0
	s_setprio 1
	v_mfma_f32_16x16x32_bf16 v[114:117], v[146:149], v[162:165], v[114:117]
	v_mfma_f32_16x16x32_bf16 v[106:109], v[154:157], v[162:165], v[106:109]
	v_mfma_f32_16x16x32_bf16 v[102:105], v[146:149], v[180:183], v[102:105]
	v_mfma_f32_16x16x32_bf16 v[94:97], v[154:157], v[180:183], v[94:97]
	v_mfma_f32_16x16x32_bf16 v[86:89], v[146:149], v[206:209], v[86:89]
	v_mfma_f32_16x16x32_bf16 v[78:81], v[154:157], v[206:209], v[78:81]
	v_mfma_f32_16x16x32_bf16 v[70:73], v[146:149], v[214:217], v[70:73]
	v_mfma_f32_16x16x32_bf16 v[66:69], v[154:157], v[214:217], v[66:69]
	v_mfma_f32_16x16x32_bf16 v[114:117], v[150:153], v[176:179], v[114:117]
	v_mfma_f32_16x16x32_bf16 v[106:109], v[158:161], v[176:179], v[106:109]
	v_mfma_f32_16x16x32_bf16 v[102:105], v[150:153], v[184:187], v[102:105]
	v_mfma_f32_16x16x32_bf16 v[94:97], v[158:161], v[184:187], v[94:97]
	v_mfma_f32_16x16x32_bf16 v[86:89], v[150:153], v[210:213], v[86:89]
	v_mfma_f32_16x16x32_bf16 v[78:81], v[158:161], v[210:213], v[78:81]
	v_mfma_f32_16x16x32_bf16 v[70:73], v[150:153], v[218:221], v[70:73]
	v_mfma_f32_16x16x32_bf16 v[66:69], v[158:161], v[218:221], v[66:69]
	s_setprio 0
	s_barrier
	s_add_u32 s100, s40, 0xfff80080
	s_addc_u32 s101, s41, -1
	s_add_u32 s98, s42, 0x80
	s_addc_u32 s99, s43, 0
	s_add_i32 s33, s33, s19
	s_mov_b32 m0, s33
	ds_read_b128 v[162:165], v204 offset:49152
	ds_read_b128 v[176:179], v204 offset:50176
	ds_read_b128 v[180:183], v204 offset:51200
	ds_read_b128 v[184:187], v204 offset:52224
	ds_read_b128 v[206:209], v204 offset:53248
	ds_read_b128 v[210:213], v204 offset:54272
	ds_read_b128 v[214:217], v204 offset:55296
	ds_read_b128 v[218:221], v204 offset:56320
	global_load_lds_dwordx4 v0, s[98:99]
	s_add_i32 m0, s33, 0x2000
	s_add_u32 s40, s42, 0x80080
	s_addc_u32 s41, s43, 0
	s_add_i32 s33, s44, s19
	global_load_lds_dwordx4 v170, s[98:99]
	s_mov_b32 m0, s33
	s_nop 0
	global_load_lds_dwordx4 v0, s[40:41]
	s_add_i32 m0, s33, 0x2000
	s_nop 0
	global_load_lds_dwordx4 v170, s[40:41]
	s_mov_b32 m0, s54
	s_nop 0
	global_load_lds_dwordx4 v166, s[100:101]
	s_mov_b32 m0, s55
	s_nop 0
	global_load_lds_dwordx4 v168, s[100:101]
	s_waitcnt vmcnt(8)
	s_waitcnt lgkmcnt(0)
	s_barrier
	s_setprio 1
	s_waitcnt lgkmcnt(0)
	v_mfma_f32_16x16x32_bf16 v[62:65], v[122:125], v[162:165], v[62:65]
	v_mfma_f32_16x16x32_bf16 v[58:61], v[130:133], v[162:165], v[58:61]
	v_mfma_f32_16x16x32_bf16 v[50:53], v[122:125], v[180:183], v[50:53]
	v_mfma_f32_16x16x32_bf16 v[42:45], v[130:133], v[180:183], v[42:45]
	v_mfma_f32_16x16x32_bf16 v[34:37], v[122:125], v[206:209], v[34:37]
	v_mfma_f32_16x16x32_bf16 v[26:29], v[130:133], v[206:209], v[26:29]
	v_mfma_f32_16x16x32_bf16 v[18:21], v[122:125], v[214:217], v[18:21]
	v_mfma_f32_16x16x32_bf16 v[10:13], v[130:133], v[214:217], v[10:13]
	v_mfma_f32_16x16x32_bf16 v[62:65], v[126:129], v[176:179], v[62:65]
	v_mfma_f32_16x16x32_bf16 v[58:61], v[134:137], v[176:179], v[58:61]
	v_mfma_f32_16x16x32_bf16 v[50:53], v[126:129], v[184:187], v[50:53]
	v_mfma_f32_16x16x32_bf16 v[42:45], v[134:137], v[184:187], v[42:45]
	v_mfma_f32_16x16x32_bf16 v[34:37], v[126:129], v[210:213], v[34:37]
	v_mfma_f32_16x16x32_bf16 v[26:29], v[134:137], v[210:213], v[26:29]
	v_mfma_f32_16x16x32_bf16 v[18:21], v[126:129], v[218:221], v[18:21]
	v_mfma_f32_16x16x32_bf16 v[10:13], v[134:137], v[218:221], v[10:13]
	s_setprio 0
	s_setprio 1
	v_mfma_f32_16x16x32_bf16 v[54:57], v[146:149], v[162:165], v[54:57]
	v_mfma_f32_16x16x32_bf16 v[46:49], v[154:157], v[162:165], v[46:49]
	v_mfma_f32_16x16x32_bf16 v[38:41], v[146:149], v[180:183], v[38:41]
	v_mfma_f32_16x16x32_bf16 v[30:33], v[154:157], v[180:183], v[30:33]
	v_mfma_f32_16x16x32_bf16 v[22:25], v[146:149], v[206:209], v[22:25]
	v_mfma_f32_16x16x32_bf16 v[14:17], v[154:157], v[206:209], v[14:17]
	v_mfma_f32_16x16x32_bf16 v[6:9], v[146:149], v[214:217], v[6:9]
	v_mfma_f32_16x16x32_bf16 v[2:5], v[154:157], v[214:217], v[2:5]
	v_mfma_f32_16x16x32_bf16 v[54:57], v[150:153], v[176:179], v[54:57]
	v_mfma_f32_16x16x32_bf16 v[46:49], v[158:161], v[176:179], v[46:49]
	v_mfma_f32_16x16x32_bf16 v[38:41], v[150:153], v[184:187], v[38:41]
	v_mfma_f32_16x16x32_bf16 v[30:33], v[158:161], v[184:187], v[30:33]
	v_mfma_f32_16x16x32_bf16 v[22:25], v[150:153], v[210:213], v[22:25]
	v_mfma_f32_16x16x32_bf16 v[14:17], v[158:161], v[210:213], v[14:17]
	v_mfma_f32_16x16x32_bf16 v[6:9], v[150:153], v[218:221], v[6:9]
	v_mfma_f32_16x16x32_bf16 v[2:5], v[158:161], v[218:221], v[2:5]
	s_setprio 0
	s_barrier
	s_add_u32 s38, s38, 0x100
	s_addc_u32 s39, s39, 0
	s_add_u32 s15, s15, 0x100
	s_addc_u32 s21, s21, 0
	s_cmp_ge_u32 s37, s27
	s_mov_b32 s33, s37
	s_cbranch_scc0 .LBB0_977
	s_branch .Lpeel_exit_3

.Lpeel_exit_3:
	s_and_b64 vcc, exec, s[10:11]
	s_cbranch_vccz .LBB0_980
	s_barrier

.LBB0_1079:
	s_ashr_i32 s43, s42, 31
	s_lshl_b64 s[40:41], s[42:43], 20
	s_add_u32 s50, s19, s40
	s_addc_u32 s51, s28, s41
	s_and_b64 s[40:41], s[8:9], exec
	s_cselect_b32 s11, s51, s57
	s_cselect_b32 s33, s50, s56
	s_ashr_i32 s39, s38, 31
	s_lshl_b64 s[40:41], s[38:39], 20
	s_add_u32 s52, s29, s40
	s_addc_u32 s53, s34, s41
	s_and_b64 s[40:41], s[8:9], exec
	s_cselect_b32 s39, s53, s61
	s_cselect_b32 s40, s52, s60
	s_add_u32 s41, s60, 0x100
	s_addc_u32 s43, s61, 0
	s_mov_b32 s44, -2
	v_add_u32_e32 v253, 0x10000, v223
	s_add_u32 s60, s56, 0x100
	s_addc_u32 s61, s57, 0
	s_add_i32 s45, 0, 0x10000
	s_cmp_eq_u32 s44, 28
	s_cselect_b32 s65, s11, s61
	s_cselect_b32 s64, s33, s60
	s_cselect_b32 s63, s39, s43
	s_cselect_b32 s62, s40, s41
	s_add_i32 s55, 0, 0x14000
	ds_read_b128 v[62:65], v253
	ds_read_b128 v[66:69], v253 offset:1024
	ds_read_b128 v[106:109], v253 offset:2048
	ds_read_b128 v[110:113], v253 offset:3072
	ds_read_b128 v[138:141], v253 offset:16384
	ds_read_b128 v[150:153], v253 offset:17408
	ds_read_b128 v[154:157], v253 offset:18432
	ds_read_b128 v[158:161], v253 offset:19456
	s_add_i32 m0, s46, 0xc000
	ds_read_b128 v[162:165], v227
	ds_read_b128 v[166:169], v227 offset:1024
	ds_read_b128 v[170:173], v227 offset:2048
	ds_read_b128 v[174:177], v227 offset:3072
	ds_read_b128 v[178:181], v227 offset:4096
	ds_read_b128 v[182:185], v227 offset:5120
	ds_read_b128 v[186:189], v227 offset:6144
	ds_read_b128 v[190:193], v227 offset:7168
	global_load_lds_dwordx4 v210, s[56:57]
	s_add_i32 m0, s46, 0xe000
	s_nop 0
	global_load_lds_dwordx4 v212, s[56:57]
	s_waitcnt vmcnt(8)
	s_waitcnt lgkmcnt(0)
	s_barrier
	s_setprio 1
	s_waitcnt lgkmcnt(0)
	v_mfma_f32_16x16x32_bf16 v[146:149], v[62:65], v[162:165], 0
	v_mfma_f32_16x16x32_bf16 v[70:73], v[106:109], v[162:165], 0
	v_mfma_f32_16x16x32_bf16 v[134:137], v[62:65], v[170:173], 0
	v_mfma_f32_16x16x32_bf16 v[54:57], v[106:109], v[170:173], 0
	v_mfma_f32_16x16x32_bf16 v[126:129], v[62:65], v[178:181], 0
	v_mfma_f32_16x16x32_bf16 v[46:49], v[106:109], v[178:181], 0
	v_mfma_f32_16x16x32_bf16 v[118:121], v[62:65], v[186:189], 0
	v_mfma_f32_16x16x32_bf16 v[38:41], v[106:109], v[186:189], 0
	v_mfma_f32_16x16x32_bf16 v[146:149], v[66:69], v[166:169], v[146:149]
	v_mfma_f32_16x16x32_bf16 v[70:73], v[110:113], v[166:169], v[70:73]
	v_mfma_f32_16x16x32_bf16 v[134:137], v[66:69], v[174:177], v[134:137]
	v_mfma_f32_16x16x32_bf16 v[54:57], v[110:113], v[174:177], v[54:57]
	v_mfma_f32_16x16x32_bf16 v[126:129], v[66:69], v[182:185], v[126:129]
	v_mfma_f32_16x16x32_bf16 v[46:49], v[110:113], v[182:185], v[46:49]
	v_mfma_f32_16x16x32_bf16 v[118:121], v[66:69], v[190:193], v[118:121]
	v_mfma_f32_16x16x32_bf16 v[38:41], v[110:113], v[190:193], v[38:41]
	s_setprio 0
	s_setprio 1
	v_mfma_f32_16x16x32_bf16 v[142:145], v[138:141], v[162:165], 0
	v_mfma_f32_16x16x32_bf16 v[58:61], v[154:157], v[162:165], 0
	v_mfma_f32_16x16x32_bf16 v[130:133], v[138:141], v[170:173], 0
	v_mfma_f32_16x16x32_bf16 v[50:53], v[154:157], v[170:173], 0
	v_mfma_f32_16x16x32_bf16 v[122:125], v[138:141], v[178:181], 0
	v_mfma_f32_16x16x32_bf16 v[42:45], v[154:157], v[178:181], 0
	v_mfma_f32_16x16x32_bf16 v[114:117], v[138:141], v[186:189], 0
	v_mfma_f32_16x16x32_bf16 v[34:37], v[154:157], v[186:189], 0
	v_mfma_f32_16x16x32_bf16 v[142:145], v[150:153], v[166:169], v[142:145]
	v_mfma_f32_16x16x32_bf16 v[58:61], v[158:161], v[166:169], v[58:61]
	v_mfma_f32_16x16x32_bf16 v[130:133], v[150:153], v[174:177], v[130:133]
	v_mfma_f32_16x16x32_bf16 v[50:53], v[158:161], v[174:177], v[50:53]
	v_mfma_f32_16x16x32_bf16 v[122:125], v[150:153], v[182:185], v[122:125]
	v_mfma_f32_16x16x32_bf16 v[42:45], v[158:161], v[182:185], v[42:45]
	v_mfma_f32_16x16x32_bf16 v[114:117], v[150:153], v[190:193], v[114:117]
	v_mfma_f32_16x16x32_bf16 v[34:37], v[158:161], v[190:193], v[34:37]
	s_setprio 0
	s_barrier
	s_add_i32 s45, s45, s35
	s_mov_b32 m0, s45
	ds_read_b128 v[162:165], v227 offset:16384
	ds_read_b128 v[166:169], v227 offset:17408
	ds_read_b128 v[170:173], v227 offset:18432
	ds_read_b128 v[174:177], v227 offset:19456
	ds_read_b128 v[178:181], v227 offset:20480
	ds_read_b128 v[182:185], v227 offset:21504
	ds_read_b128 v[186:189], v227 offset:22528
	ds_read_b128 v[190:193], v227 offset:23552
	global_load_lds_dwordx4 v0, s[62:63]
	s_add_i32 m0, s45, 0x2000
	s_add_u32 s56, s62, 0x80000
	s_addc_u32 s57, s63, 0
	s_add_i32 s45, s55, s35
	global_load_lds_dwordx4 v208, s[62:63]
	s_mov_b32 m0, s45
	s_nop 0
	global_load_lds_dwordx4 v0, s[56:57]
	s_add_i32 m0, s45, 0x2000
	s_nop 0
	global_load_lds_dwordx4 v208, s[56:57]
	s_mov_b32 m0, s46
	s_nop 0
	global_load_lds_dwordx4 v204, s[64:65]
	s_mov_b32 m0, s66
	s_nop 0
	global_load_lds_dwordx4 v206, s[64:65]
	s_waitcnt vmcnt(8)
	s_waitcnt lgkmcnt(0)
	s_barrier
	s_setprio 1
	s_waitcnt lgkmcnt(0)
	v_mfma_f32_16x16x32_bf16 v[102:105], v[62:65], v[162:165], 0
	v_mfma_f32_16x16x32_bf16 v[30:33], v[106:109], v[162:165], 0
	v_mfma_f32_16x16x32_bf16 v[94:97], v[62:65], v[170:173], 0
	v_mfma_f32_16x16x32_bf16 v[22:25], v[106:109], v[170:173], 0
	v_mfma_f32_16x16x32_bf16 v[86:89], v[62:65], v[178:181], 0
	v_mfma_f32_16x16x32_bf16 v[14:17], v[106:109], v[178:181], 0
	v_mfma_f32_16x16x32_bf16 v[10:13], v[106:109], v[186:189], 0
	v_mfma_f32_16x16x32_bf16 v[102:105], v[66:69], v[166:169], v[102:105]
	v_mfma_f32_16x16x32_bf16 v[30:33], v[110:113], v[166:169], v[30:33]
	v_mfma_f32_16x16x32_bf16 v[94:97], v[66:69], v[174:177], v[94:97]
	v_mfma_f32_16x16x32_bf16 v[22:25], v[110:113], v[174:177], v[22:25]
	v_mfma_f32_16x16x32_bf16 v[86:89], v[66:69], v[182:185], v[86:89]
	v_mfma_f32_16x16x32_bf16 v[14:17], v[110:113], v[182:185], v[14:17]
	v_mfma_f32_16x16x32_bf16 v[62:65], v[62:65], v[186:189], 0
	v_mfma_f32_16x16x32_bf16 v[10:13], v[110:113], v[190:193], v[10:13]
	v_mfma_f32_16x16x32_bf16 v[62:65], v[66:69], v[190:193], v[62:65]
	s_setprio 0
	s_setprio 1
	v_mfma_f32_16x16x32_bf16 v[26:29], v[154:157], v[162:165], 0
	v_mfma_f32_16x16x32_bf16 v[82:85], v[138:141], v[170:173], 0
	v_mfma_f32_16x16x32_bf16 v[18:21], v[154:157], v[170:173], 0
	v_mfma_f32_16x16x32_bf16 v[78:81], v[138:141], v[178:181], 0
	v_mfma_f32_16x16x32_bf16 v[6:9], v[154:157], v[178:181], 0
	v_mfma_f32_16x16x32_bf16 v[74:77], v[138:141], v[186:189], 0
	v_mfma_f32_16x16x32_bf16 v[2:5], v[154:157], v[186:189], 0
	v_mfma_f32_16x16x32_bf16 v[66:69], v[138:141], v[162:165], 0
	v_mfma_f32_16x16x32_bf16 v[26:29], v[158:161], v[166:169], v[26:29]
	v_mfma_f32_16x16x32_bf16 v[90:93], v[150:153], v[174:177], v[82:85]
	v_mfma_f32_16x16x32_bf16 v[18:21], v[158:161], v[174:177], v[18:21]
	v_mfma_f32_16x16x32_bf16 v[78:81], v[150:153], v[182:185], v[78:81]
	v_mfma_f32_16x16x32_bf16 v[6:9], v[158:161], v[182:185], v[6:9]
	v_mfma_f32_16x16x32_bf16 v[74:77], v[150:153], v[190:193], v[74:77]
	v_mfma_f32_16x16x32_bf16 v[2:5], v[158:161], v[190:193], v[2:5]
	v_mfma_f32_16x16x32_bf16 v[66:69], v[150:153], v[166:169], v[66:69]
	s_setprio 0
	s_barrier
	s_add_i32 s45, 0, 0x18000
	s_add_i32 s55, 0, 0x1c000
	ds_read_b128 v[82:85], v253 offset:32768
	ds_read_b128 v[98:101], v253 offset:33792
	ds_read_b128 v[106:109], v253 offset:34816
	ds_read_b128 v[110:113], v253 offset:35840
	ds_read_b128 v[138:141], v253 offset:49152
	ds_read_b128 v[150:153], v253 offset:50176
	ds_read_b128 v[154:157], v253 offset:51200
	ds_read_b128 v[158:161], v253 offset:52224
	s_add_u32 s56, s64, 0x4000
	s_addc_u32 s57, s65, 0
	s_mov_b32 m0, s67
	ds_read_b128 v[162:165], v227 offset:32768
	ds_read_b128 v[166:169], v227 offset:33792
	ds_read_b128 v[170:173], v227 offset:34816
	ds_read_b128 v[174:177], v227 offset:35840
	ds_read_b128 v[178:181], v227 offset:36864
	ds_read_b128 v[182:185], v227 offset:37888
	ds_read_b128 v[186:189], v227 offset:38912
	ds_read_b128 v[190:193], v227 offset:39936
	global_load_lds_dwordx4 v204, s[56:57]
	s_mov_b32 m0, s68
	s_nop 0
	global_load_lds_dwordx4 v206, s[56:57]
	s_waitcnt vmcnt(8)
	s_waitcnt lgkmcnt(0)
	s_barrier
	s_setprio 1
	s_waitcnt lgkmcnt(0)
	v_mfma_f32_16x16x32_bf16 v[146:149], v[82:85], v[162:165], v[146:149]
	v_mfma_f32_16x16x32_bf16 v[70:73], v[106:109], v[162:165], v[70:73]
	v_mfma_f32_16x16x32_bf16 v[134:137], v[82:85], v[170:173], v[134:137]
	v_mfma_f32_16x16x32_bf16 v[54:57], v[106:109], v[170:173], v[54:57]
	v_mfma_f32_16x16x32_bf16 v[126:129], v[82:85], v[178:181], v[126:129]
	v_mfma_f32_16x16x32_bf16 v[46:49], v[106:109], v[178:181], v[46:49]
	v_mfma_f32_16x16x32_bf16 v[118:121], v[82:85], v[186:189], v[118:121]
	v_mfma_f32_16x16x32_bf16 v[38:41], v[106:109], v[186:189], v[38:41]
	v_mfma_f32_16x16x32_bf16 v[146:149], v[98:101], v[166:169], v[146:149]
	v_mfma_f32_16x16x32_bf16 v[70:73], v[110:113], v[166:169], v[70:73]
	v_mfma_f32_16x16x32_bf16 v[134:137], v[98:101], v[174:177], v[134:137]
	v_mfma_f32_16x16x32_bf16 v[54:57], v[110:113], v[174:177], v[54:57]
	v_mfma_f32_16x16x32_bf16 v[126:129], v[98:101], v[182:185], v[126:129]
	v_mfma_f32_16x16x32_bf16 v[46:49], v[110:113], v[182:185], v[46:49]
	v_mfma_f32_16x16x32_bf16 v[118:121], v[98:101], v[190:193], v[118:121]
	v_mfma_f32_16x16x32_bf16 v[38:41], v[110:113], v[190:193], v[38:41]
	s_setprio 0
	s_setprio 1
	v_mfma_f32_16x16x32_bf16 v[142:145], v[138:141], v[162:165], v[142:145]
	v_mfma_f32_16x16x32_bf16 v[58:61], v[154:157], v[162:165], v[58:61]
	v_mfma_f32_16x16x32_bf16 v[130:133], v[138:141], v[170:173], v[130:133]
	v_mfma_f32_16x16x32_bf16 v[50:53], v[154:157], v[170:173], v[50:53]
	v_mfma_f32_16x16x32_bf16 v[122:125], v[138:141], v[178:181], v[122:125]
	v_mfma_f32_16x16x32_bf16 v[42:45], v[154:157], v[178:181], v[42:45]
	v_mfma_f32_16x16x32_bf16 v[114:117], v[138:141], v[186:189], v[114:117]
	v_mfma_f32_16x16x32_bf16 v[34:37], v[154:157], v[186:189], v[34:37]
	v_mfma_f32_16x16x32_bf16 v[142:145], v[150:153], v[166:169], v[142:145]
	v_mfma_f32_16x16x32_bf16 v[58:61], v[158:161], v[166:169], v[58:61]
	v_mfma_f32_16x16x32_bf16 v[130:133], v[150:153], v[174:177], v[130:133]
	v_mfma_f32_16x16x32_bf16 v[50:53], v[158:161], v[174:177], v[50:53]
	v_mfma_f32_16x16x32_bf16 v[122:125], v[150:153], v[182:185], v[122:125]
	v_mfma_f32_16x16x32_bf16 v[42:45], v[158:161], v[182:185], v[42:45]
	v_mfma_f32_16x16x32_bf16 v[114:117], v[150:153], v[190:193], v[114:117]
	v_mfma_f32_16x16x32_bf16 v[34:37], v[158:161], v[190:193], v[34:37]
	s_setprio 0
	s_barrier
	s_add_u32 s100, s56, 0xffffc080
	s_addc_u32 s101, s57, -1
	s_add_u32 s98, s62, 0x80
	s_addc_u32 s99, s63, 0
	s_add_i32 s45, s45, s35
	s_mov_b32 m0, s45
	ds_read_b128 v[162:165], v227 offset:49152
	ds_read_b128 v[166:169], v227 offset:50176
	ds_read_b128 v[170:173], v227 offset:51200
	ds_read_b128 v[174:177], v227 offset:52224
	ds_read_b128 v[178:181], v227 offset:53248
	ds_read_b128 v[182:185], v227 offset:54272
	ds_read_b128 v[186:189], v227 offset:55296
	ds_read_b128 v[190:193], v227 offset:56320
	global_load_lds_dwordx4 v0, s[98:99]
	s_add_i32 m0, s45, 0x2000
	s_add_u32 s56, s62, 0x80080
	s_addc_u32 s57, s63, 0
	s_add_i32 s45, s55, s35
	global_load_lds_dwordx4 v208, s[98:99]
	s_mov_b32 m0, s45
	s_nop 0
	global_load_lds_dwordx4 v0, s[56:57]
	s_add_i32 m0, s45, 0x2000
	s_nop 0
	global_load_lds_dwordx4 v208, s[56:57]
	s_mov_b32 m0, s71
	s_nop 0
	global_load_lds_dwordx4 v204, s[100:101]
	s_mov_b32 m0, s74
	s_nop 0
	global_load_lds_dwordx4 v206, s[100:101]
	s_waitcnt vmcnt(8)
	s_waitcnt lgkmcnt(0)
	s_barrier
	s_setprio 1
	s_waitcnt lgkmcnt(0)
	v_mfma_f32_16x16x32_bf16 v[102:105], v[82:85], v[162:165], v[102:105]
	v_mfma_f32_16x16x32_bf16 v[30:33], v[106:109], v[162:165], v[30:33]
	v_mfma_f32_16x16x32_bf16 v[94:97], v[82:85], v[170:173], v[94:97]
	v_mfma_f32_16x16x32_bf16 v[22:25], v[106:109], v[170:173], v[22:25]
	v_mfma_f32_16x16x32_bf16 v[86:89], v[82:85], v[178:181], v[86:89]
	v_mfma_f32_16x16x32_bf16 v[14:17], v[106:109], v[178:181], v[14:17]
	v_mfma_f32_16x16x32_bf16 v[62:65], v[82:85], v[186:189], v[62:65]
	v_mfma_f32_16x16x32_bf16 v[10:13], v[106:109], v[186:189], v[10:13]
	v_mfma_f32_16x16x32_bf16 v[102:105], v[98:101], v[166:169], v[102:105]
	v_mfma_f32_16x16x32_bf16 v[30:33], v[110:113], v[166:169], v[30:33]
	v_mfma_f32_16x16x32_bf16 v[94:97], v[98:101], v[174:177], v[94:97]
	v_mfma_f32_16x16x32_bf16 v[22:25], v[110:113], v[174:177], v[22:25]
	v_mfma_f32_16x16x32_bf16 v[86:89], v[98:101], v[182:185], v[86:89]
	v_mfma_f32_16x16x32_bf16 v[14:17], v[110:113], v[182:185], v[14:17]
	v_mfma_f32_16x16x32_bf16 v[82:85], v[98:101], v[190:193], v[62:65]
	v_mfma_f32_16x16x32_bf16 v[10:13], v[110:113], v[190:193], v[10:13]
	s_setprio 0
	s_setprio 1
	v_mfma_f32_16x16x32_bf16 v[62:65], v[138:141], v[162:165], v[66:69]
	v_mfma_f32_16x16x32_bf16 v[98:101], v[150:153], v[166:169], v[62:65]
	v_mfma_f32_16x16x32_bf16 v[62:65], v[138:141], v[170:173], v[90:93]
	v_mfma_f32_16x16x32_bf16 v[90:93], v[150:153], v[174:177], v[62:65]
	v_mfma_f32_16x16x32_bf16 v[62:65], v[138:141], v[178:181], v[78:81]
	v_mfma_f32_16x16x32_bf16 v[26:29], v[154:157], v[162:165], v[26:29]
	v_mfma_f32_16x16x32_bf16 v[18:21], v[154:157], v[170:173], v[18:21]
	v_mfma_f32_16x16x32_bf16 v[78:81], v[150:153], v[182:185], v[62:65]
	v_mfma_f32_16x16x32_bf16 v[6:9], v[154:157], v[178:181], v[6:9]
	v_mfma_f32_16x16x32_bf16 v[62:65], v[138:141], v[186:189], v[74:77]
	v_mfma_f32_16x16x32_bf16 v[2:5], v[154:157], v[186:189], v[2:5]
	v_mfma_f32_16x16x32_bf16 v[26:29], v[158:161], v[166:169], v[26:29]
	v_mfma_f32_16x16x32_bf16 v[18:21], v[158:161], v[174:177], v[18:21]
	v_mfma_f32_16x16x32_bf16 v[6:9], v[158:161], v[182:185], v[6:9]
	v_mfma_f32_16x16x32_bf16 v[74:77], v[150:153], v[190:193], v[62:65]
	v_mfma_f32_16x16x32_bf16 v[2:5], v[158:161], v[190:193], v[2:5]
	s_setprio 0
	s_barrier
	s_add_i32 s44, s44, 2
	s_add_u32 s41, s41, 0x100
	s_addc_u32 s43, s43, 0
	s_cmp_gt_u32 s44, 29
	s_mov_b64 s[56:57], s[60:61]
	s_cbranch_scc0 .LBB0_1080
	s_branch .Lpeel_exit_4

.Lpeel_exit_4:
	s_and_b64 vcc, exec, s[24:25]
	s_cbranch_vccz .LBB0_1083
	s_barrier

.LBB0_1185:
	s_add_i32 s13, s55, -2
	s_add_u32 s33, s24, 0x100
	s_addc_u32 s40, s25, 0
	s_mov_b32 s26, 0
	v_add_u32_e32 v253, 0x10000, v190
	s_add_i32 s41, s26, 2
	s_add_u32 s24, s22, 0x100
	s_addc_u32 s25, s23, 0
	s_add_i32 s44, 0, 0x10000
	s_cmp_eq_u32 s13, s26
	s_cselect_b32 s31, s15, s25
	s_cselect_b32 s30, s14, s24
	s_cselect_b32 s27, s17, s40
	s_cselect_b32 s26, s16, s33
	s_add_i32 s45, 0, 0x14000
	ds_read_b128 v[102:105], v253
	ds_read_b128 v[106:109], v253 offset:1024
	ds_read_b128 v[110:113], v253 offset:2048
	ds_read_b128 v[118:121], v253 offset:3072
	ds_read_b128 v[146:149], v253 offset:16384
	ds_read_b128 v[150:153], v253 offset:17408
	ds_read_b128 v[154:157], v253 offset:18432
	ds_read_b128 v[158:161], v253 offset:19456
	s_add_i32 m0, s34, 0xc000
	ds_read_b128 v[162:165], v192
	ds_read_b128 v[176:179], v192 offset:1024
	ds_read_b128 v[180:183], v192 offset:2048
	ds_read_b128 v[184:187], v192 offset:3072
	ds_read_b128 v[204:207], v192 offset:4096
	ds_read_b128 v[208:211], v192 offset:5120
	ds_read_b128 v[212:215], v192 offset:6144
	ds_read_b128 v[216:219], v192 offset:7168
	global_load_lds_dwordx4 v172, s[22:23]
	s_add_i32 m0, s34, 0xe000
	s_nop 0
	global_load_lds_dwordx4 v174, s[22:23]
	s_waitcnt vmcnt(8)
	s_waitcnt lgkmcnt(0)
	s_barrier
	s_setprio 1
	s_waitcnt lgkmcnt(0)
	v_mfma_f32_16x16x32_bf16 v[142:145], v[102:105], v[162:165], 0
	v_mfma_f32_16x16x32_bf16 v[138:141], v[110:113], v[162:165], 0
	v_mfma_f32_16x16x32_bf16 v[134:137], v[102:105], v[180:183], 0
	v_mfma_f32_16x16x32_bf16 v[126:129], v[110:113], v[180:183], 0
	v_mfma_f32_16x16x32_bf16 v[98:101], v[102:105], v[204:207], 0
	v_mfma_f32_16x16x32_bf16 v[90:93], v[110:113], v[204:207], 0
	v_mfma_f32_16x16x32_bf16 v[86:89], v[102:105], v[212:215], 0
	v_mfma_f32_16x16x32_bf16 v[78:81], v[110:113], v[212:215], 0
	v_mfma_f32_16x16x32_bf16 v[142:145], v[106:109], v[176:179], v[142:145]
	v_mfma_f32_16x16x32_bf16 v[138:141], v[118:121], v[176:179], v[138:141]
	v_mfma_f32_16x16x32_bf16 v[134:137], v[106:109], v[184:187], v[134:137]
	v_mfma_f32_16x16x32_bf16 v[126:129], v[118:121], v[184:187], v[126:129]
	v_mfma_f32_16x16x32_bf16 v[98:101], v[106:109], v[208:211], v[98:101]
	v_mfma_f32_16x16x32_bf16 v[90:93], v[118:121], v[208:211], v[90:93]
	v_mfma_f32_16x16x32_bf16 v[86:89], v[106:109], v[216:219], v[86:89]
	v_mfma_f32_16x16x32_bf16 v[78:81], v[118:121], v[216:219], v[78:81]
	s_setprio 0
	s_setprio 1
	v_mfma_f32_16x16x32_bf16 v[130:133], v[146:149], v[162:165], 0
	v_mfma_f32_16x16x32_bf16 v[122:125], v[154:157], v[162:165], 0
	v_mfma_f32_16x16x32_bf16 v[114:117], v[146:149], v[180:183], 0
	v_mfma_f32_16x16x32_bf16 v[94:97], v[154:157], v[180:183], 0
	v_mfma_f32_16x16x32_bf16 v[82:85], v[146:149], v[204:207], 0
	v_mfma_f32_16x16x32_bf16 v[74:77], v[154:157], v[204:207], 0
	v_mfma_f32_16x16x32_bf16 v[70:73], v[146:149], v[212:215], 0
	v_mfma_f32_16x16x32_bf16 v[66:69], v[154:157], v[212:215], 0
	v_mfma_f32_16x16x32_bf16 v[130:133], v[150:153], v[176:179], v[130:133]
	v_mfma_f32_16x16x32_bf16 v[122:125], v[158:161], v[176:179], v[122:125]
	v_mfma_f32_16x16x32_bf16 v[114:117], v[150:153], v[184:187], v[114:117]
	v_mfma_f32_16x16x32_bf16 v[94:97], v[158:161], v[184:187], v[94:97]
	v_mfma_f32_16x16x32_bf16 v[82:85], v[150:153], v[208:211], v[82:85]
	v_mfma_f32_16x16x32_bf16 v[74:77], v[158:161], v[208:211], v[74:77]
	v_mfma_f32_16x16x32_bf16 v[70:73], v[150:153], v[216:219], v[70:73]
	v_mfma_f32_16x16x32_bf16 v[66:69], v[158:161], v[216:219], v[66:69]
	s_setprio 0
	s_barrier
	s_add_i32 s22, s44, s29
	s_mov_b32 m0, s22
	ds_read_b128 v[162:165], v192 offset:16384
	ds_read_b128 v[176:179], v192 offset:17408
	ds_read_b128 v[180:183], v192 offset:18432
	ds_read_b128 v[184:187], v192 offset:19456
	ds_read_b128 v[204:207], v192 offset:20480
	ds_read_b128 v[208:211], v192 offset:21504
	ds_read_b128 v[212:215], v192 offset:22528
	ds_read_b128 v[216:219], v192 offset:23552
	global_load_lds_dwordx4 v0, s[26:27]
	s_add_i32 m0, s22, 0x2000
	s_add_u32 s22, s26, 0x160000
	s_addc_u32 s23, s27, 0
	s_add_i32 s44, s45, s29
	global_load_lds_dwordx4 v170, s[26:27]
	s_mov_b32 m0, s44
	s_nop 0
	global_load_lds_dwordx4 v0, s[22:23]
	s_add_i32 m0, s44, 0x2000
	s_nop 0
	global_load_lds_dwordx4 v170, s[22:23]
	s_mov_b32 m0, s34
	s_nop 0
	global_load_lds_dwordx4 v166, s[30:31]
	s_mov_b32 m0, s35
	s_nop 0
	global_load_lds_dwordx4 v168, s[30:31]
	s_waitcnt vmcnt(8)
	s_waitcnt lgkmcnt(0)
	s_barrier
	s_setprio 1
	s_waitcnt lgkmcnt(0)
	v_mfma_f32_16x16x32_bf16 v[62:65], v[102:105], v[162:165], 0
	v_mfma_f32_16x16x32_bf16 v[58:61], v[110:113], v[162:165], 0
	v_mfma_f32_16x16x32_bf16 v[50:53], v[102:105], v[180:183], 0
	v_mfma_f32_16x16x32_bf16 v[42:45], v[110:113], v[180:183], 0
	v_mfma_f32_16x16x32_bf16 v[34:37], v[102:105], v[204:207], 0
	v_mfma_f32_16x16x32_bf16 v[26:29], v[110:113], v[204:207], 0
	v_mfma_f32_16x16x32_bf16 v[18:21], v[102:105], v[212:215], 0
	v_mfma_f32_16x16x32_bf16 v[10:13], v[110:113], v[212:215], 0
	v_mfma_f32_16x16x32_bf16 v[62:65], v[106:109], v[176:179], v[62:65]
	v_mfma_f32_16x16x32_bf16 v[58:61], v[118:121], v[176:179], v[58:61]
	v_mfma_f32_16x16x32_bf16 v[50:53], v[106:109], v[184:187], v[50:53]
	v_mfma_f32_16x16x32_bf16 v[42:45], v[118:121], v[184:187], v[42:45]
	v_mfma_f32_16x16x32_bf16 v[34:37], v[106:109], v[208:211], v[34:37]
	v_mfma_f32_16x16x32_bf16 v[26:29], v[118:121], v[208:211], v[26:29]
	v_mfma_f32_16x16x32_bf16 v[18:21], v[106:109], v[216:219], v[18:21]
	v_mfma_f32_16x16x32_bf16 v[10:13], v[118:121], v[216:219], v[10:13]
	s_setprio 0
	s_setprio 1
	v_mfma_f32_16x16x32_bf16 v[54:57], v[146:149], v[162:165], 0
	v_mfma_f32_16x16x32_bf16 v[46:49], v[154:157], v[162:165], 0
	v_mfma_f32_16x16x32_bf16 v[38:41], v[146:149], v[180:183], 0
	v_mfma_f32_16x16x32_bf16 v[30:33], v[154:157], v[180:183], 0
	v_mfma_f32_16x16x32_bf16 v[22:25], v[146:149], v[204:207], 0
	v_mfma_f32_16x16x32_bf16 v[14:17], v[154:157], v[204:207], 0
	v_mfma_f32_16x16x32_bf16 v[6:9], v[146:149], v[212:215], 0
	v_mfma_f32_16x16x32_bf16 v[2:5], v[154:157], v[212:215], 0
	v_mfma_f32_16x16x32_bf16 v[54:57], v[150:153], v[176:179], v[54:57]
	v_mfma_f32_16x16x32_bf16 v[46:49], v[158:161], v[176:179], v[46:49]
	v_mfma_f32_16x16x32_bf16 v[38:41], v[150:153], v[184:187], v[38:41]
	v_mfma_f32_16x16x32_bf16 v[30:33], v[158:161], v[184:187], v[30:33]
	v_mfma_f32_16x16x32_bf16 v[22:25], v[150:153], v[208:211], v[22:25]
	v_mfma_f32_16x16x32_bf16 v[14:17], v[158:161], v[208:211], v[14:17]
	v_mfma_f32_16x16x32_bf16 v[6:9], v[150:153], v[216:219], v[6:9]
	v_mfma_f32_16x16x32_bf16 v[2:5], v[158:161], v[216:219], v[2:5]
	s_setprio 0
	s_barrier
	s_add_i32 s44, 0, 0x18000
	s_add_i32 s45, 0, 0x1c000
	ds_read_b128 v[102:105], v253 offset:32768
	ds_read_b128 v[106:109], v253 offset:33792
	ds_read_b128 v[110:113], v253 offset:34816
	ds_read_b128 v[118:121], v253 offset:35840
	ds_read_b128 v[146:149], v253 offset:49152
	ds_read_b128 v[150:153], v253 offset:50176
	ds_read_b128 v[154:157], v253 offset:51200
	ds_read_b128 v[158:161], v253 offset:52224
	s_add_u32 s22, s30, 0x160000
	s_addc_u32 s23, s31, 0
	s_mov_b32 m0, s36
	ds_read_b128 v[162:165], v192 offset:32768
	ds_read_b128 v[176:179], v192 offset:33792
	ds_read_b128 v[180:183], v192 offset:34816
	ds_read_b128 v[184:187], v192 offset:35840
	ds_read_b128 v[204:207], v192 offset:36864
	ds_read_b128 v[208:211], v192 offset:37888
	ds_read_b128 v[212:215], v192 offset:38912
	ds_read_b128 v[216:219], v192 offset:39936
	global_load_lds_dwordx4 v166, s[22:23]
	s_mov_b32 m0, s37
	s_nop 0
	global_load_lds_dwordx4 v168, s[22:23]
	s_waitcnt vmcnt(8)
	s_waitcnt lgkmcnt(0)
	s_barrier
	s_setprio 1
	s_waitcnt lgkmcnt(0)
	v_mfma_f32_16x16x32_bf16 v[142:145], v[102:105], v[162:165], v[142:145]
	v_mfma_f32_16x16x32_bf16 v[138:141], v[110:113], v[162:165], v[138:141]
	v_mfma_f32_16x16x32_bf16 v[134:137], v[102:105], v[180:183], v[134:137]
	v_mfma_f32_16x16x32_bf16 v[126:129], v[110:113], v[180:183], v[126:129]
	v_mfma_f32_16x16x32_bf16 v[98:101], v[102:105], v[204:207], v[98:101]
	v_mfma_f32_16x16x32_bf16 v[90:93], v[110:113], v[204:207], v[90:93]
	v_mfma_f32_16x16x32_bf16 v[86:89], v[102:105], v[212:215], v[86:89]
	v_mfma_f32_16x16x32_bf16 v[78:81], v[110:113], v[212:215], v[78:81]
	v_mfma_f32_16x16x32_bf16 v[142:145], v[106:109], v[176:179], v[142:145]
	v_mfma_f32_16x16x32_bf16 v[138:141], v[118:121], v[176:179], v[138:141]
	v_mfma_f32_16x16x32_bf16 v[134:137], v[106:109], v[184:187], v[134:137]
	v_mfma_f32_16x16x32_bf16 v[126:129], v[118:121], v[184:187], v[126:129]
	v_mfma_f32_16x16x32_bf16 v[98:101], v[106:109], v[208:211], v[98:101]
	v_mfma_f32_16x16x32_bf16 v[90:93], v[118:121], v[208:211], v[90:93]
	v_mfma_f32_16x16x32_bf16 v[86:89], v[106:109], v[216:219], v[86:89]
	v_mfma_f32_16x16x32_bf16 v[78:81], v[118:121], v[216:219], v[78:81]
	s_setprio 0
	s_setprio 1
	v_mfma_f32_16x16x32_bf16 v[130:133], v[146:149], v[162:165], v[130:133]
	v_mfma_f32_16x16x32_bf16 v[122:125], v[154:157], v[162:165], v[122:125]
	v_mfma_f32_16x16x32_bf16 v[114:117], v[146:149], v[180:183], v[114:117]
	v_mfma_f32_16x16x32_bf16 v[94:97], v[154:157], v[180:183], v[94:97]
	v_mfma_f32_16x16x32_bf16 v[82:85], v[146:149], v[204:207], v[82:85]
	v_mfma_f32_16x16x32_bf16 v[74:77], v[154:157], v[204:207], v[74:77]
	v_mfma_f32_16x16x32_bf16 v[70:73], v[146:149], v[212:215], v[70:73]
	v_mfma_f32_16x16x32_bf16 v[66:69], v[154:157], v[212:215], v[66:69]
	v_mfma_f32_16x16x32_bf16 v[130:133], v[150:153], v[176:179], v[130:133]
	v_mfma_f32_16x16x32_bf16 v[122:125], v[158:161], v[176:179], v[122:125]
	v_mfma_f32_16x16x32_bf16 v[114:117], v[150:153], v[184:187], v[114:117]
	v_mfma_f32_16x16x32_bf16 v[94:97], v[158:161], v[184:187], v[94:97]
	v_mfma_f32_16x16x32_bf16 v[82:85], v[150:153], v[208:211], v[82:85]
	v_mfma_f32_16x16x32_bf16 v[74:77], v[158:161], v[208:211], v[74:77]
	v_mfma_f32_16x16x32_bf16 v[70:73], v[150:153], v[216:219], v[70:73]
	v_mfma_f32_16x16x32_bf16 v[66:69], v[158:161], v[216:219], v[66:69]
	s_setprio 0
	s_barrier
	s_add_u32 s100, s22, 0xffea0080
	s_addc_u32 s101, s23, -1
	s_add_u32 s98, s26, 0x80
	s_addc_u32 s99, s27, 0
	s_add_i32 s22, s44, s29
	s_mov_b32 m0, s22
	ds_read_b128 v[162:165], v192 offset:49152
	ds_read_b128 v[176:179], v192 offset:50176
	ds_read_b128 v[180:183], v192 offset:51200
	ds_read_b128 v[184:187], v192 offset:52224
	ds_read_b128 v[204:207], v192 offset:53248
	ds_read_b128 v[208:211], v192 offset:54272
	ds_read_b128 v[212:215], v192 offset:55296
	ds_read_b128 v[216:219], v192 offset:56320
	global_load_lds_dwordx4 v0, s[98:99]
	s_add_i32 m0, s22, 0x2000
	s_add_u32 s22, s26, 0x160080
	s_addc_u32 s23, s27, 0
	s_add_i32 s26, s45, s29
	global_load_lds_dwordx4 v170, s[98:99]
	s_mov_b32 m0, s26
	s_nop 0
	global_load_lds_dwordx4 v0, s[22:23]
	s_add_i32 m0, s26, 0x2000
	s_nop 0
	global_load_lds_dwordx4 v170, s[22:23]
	s_mov_b32 m0, s42
	s_nop 0
	global_load_lds_dwordx4 v166, s[100:101]
	s_mov_b32 m0, s43
	s_nop 0
	global_load_lds_dwordx4 v168, s[100:101]
	s_waitcnt vmcnt(8)
	s_waitcnt lgkmcnt(0)
	s_barrier
	s_setprio 1
	s_waitcnt lgkmcnt(0)
	v_mfma_f32_16x16x32_bf16 v[62:65], v[102:105], v[162:165], v[62:65]
	v_mfma_f32_16x16x32_bf16 v[58:61], v[110:113], v[162:165], v[58:61]
	v_mfma_f32_16x16x32_bf16 v[50:53], v[102:105], v[180:183], v[50:53]
	v_mfma_f32_16x16x32_bf16 v[42:45], v[110:113], v[180:183], v[42:45]
	v_mfma_f32_16x16x32_bf16 v[34:37], v[102:105], v[204:207], v[34:37]
	v_mfma_f32_16x16x32_bf16 v[26:29], v[110:113], v[204:207], v[26:29]
	v_mfma_f32_16x16x32_bf16 v[18:21], v[102:105], v[212:215], v[18:21]
	v_mfma_f32_16x16x32_bf16 v[10:13], v[110:113], v[212:215], v[10:13]
	v_mfma_f32_16x16x32_bf16 v[62:65], v[106:109], v[176:179], v[62:65]
	v_mfma_f32_16x16x32_bf16 v[58:61], v[118:121], v[176:179], v[58:61]
	v_mfma_f32_16x16x32_bf16 v[50:53], v[106:109], v[184:187], v[50:53]
	v_mfma_f32_16x16x32_bf16 v[42:45], v[118:121], v[184:187], v[42:45]
	v_mfma_f32_16x16x32_bf16 v[34:37], v[106:109], v[208:211], v[34:37]
	v_mfma_f32_16x16x32_bf16 v[26:29], v[118:121], v[208:211], v[26:29]
	v_mfma_f32_16x16x32_bf16 v[18:21], v[106:109], v[216:219], v[18:21]
	v_mfma_f32_16x16x32_bf16 v[10:13], v[118:121], v[216:219], v[10:13]
	s_setprio 0
	s_setprio 1
	v_mfma_f32_16x16x32_bf16 v[54:57], v[146:149], v[162:165], v[54:57]
	v_mfma_f32_16x16x32_bf16 v[46:49], v[154:157], v[162:165], v[46:49]
	v_mfma_f32_16x16x32_bf16 v[38:41], v[146:149], v[180:183], v[38:41]
	v_mfma_f32_16x16x32_bf16 v[30:33], v[154:157], v[180:183], v[30:33]
	v_mfma_f32_16x16x32_bf16 v[22:25], v[146:149], v[204:207], v[22:25]
	v_mfma_f32_16x16x32_bf16 v[14:17], v[154:157], v[204:207], v[14:17]
	v_mfma_f32_16x16x32_bf16 v[6:9], v[146:149], v[212:215], v[6:9]
	v_mfma_f32_16x16x32_bf16 v[2:5], v[154:157], v[212:215], v[2:5]
	v_mfma_f32_16x16x32_bf16 v[54:57], v[150:153], v[176:179], v[54:57]
	v_mfma_f32_16x16x32_bf16 v[46:49], v[158:161], v[176:179], v[46:49]
	v_mfma_f32_16x16x32_bf16 v[38:41], v[150:153], v[184:187], v[38:41]
	v_mfma_f32_16x16x32_bf16 v[30:33], v[158:161], v[184:187], v[30:33]
	v_mfma_f32_16x16x32_bf16 v[22:25], v[150:153], v[208:211], v[22:25]
	v_mfma_f32_16x16x32_bf16 v[14:17], v[158:161], v[208:211], v[14:17]
	v_mfma_f32_16x16x32_bf16 v[6:9], v[150:153], v[216:219], v[6:9]
	v_mfma_f32_16x16x32_bf16 v[2:5], v[158:161], v[216:219], v[2:5]
	s_setprio 0
	s_barrier
	s_add_u32 s33, s33, 0x100
	s_addc_u32 s40, s40, 0
	s_cmp_ge_u32 s41, s55
	s_mov_b64 s[22:23], s[24:25]
	s_mov_b32 s26, s41
	s_cbranch_scc0 .LBB0_1186
	s_branch .Lpeel_exit_5
